# additionally: attention issues both V half-row loads together (one wait) and the 4th rope-table load before the first wait
# baseline (speedup 1.0000x reference)
; #define LAS __attribute__((address_space(3)))
; DI unsigned pk2(float lo, float hi) { return f2bf(lo) | (f2bf(hi) << 16); }
; DI void attn_load_head(const bf16_t* Pb, int coloff, int b, int t0, const float* g, bool rope, float scale, const float* tab, LAS bf16_t* dst) {
;     ...
;     for (int c = 0; c < 4; ++c) { u32x2 w; w.x = pk2(y[c][0] * scale, y[c][1] * scale); w.y = pk2(y[c][2] * scale, y[c][3] * scale);
;         *(LAS u32x2*)(dst + row * 72 + c * 16 + q4 * 4) = w; }
; DI void attn_tile(int j, int tile, LAS unsigned char* lds) {
;     ...
;         { const int row = tid >> 2, q4 = tid & 3; const bf16_t* src = Pb + ((size_t)b * T + tk0 + row) * PW + 2688 + kvh * 64 + q4 * 16;
;           const u32x4 v0 = *(const u32x4*)src, v1 = *(const u32x4*)(src + 8); const unsigned vv[8] = {v0.x, v0.y, v0.z, v0.w, v1.x, v1.y, v1.z, v1.w};
; #pragma unroll
;           for (int e = 0; e < 8; ++e) { VTs[(q4 * 16 + 2 * e) * 136 + row] = (bf16_t)(vv[e] & 0xffff); VTs[(q4 * 16 + 2 * e + 1) * 136 + row] = (bf16_t)(vv[e] >> 16); } }
;         __syncthreads();
.LBB0_609:
	s_movk_i32 s2, 0x90
	v_mul_lo_u32 v88, v90, s2
	s_mov_b32 s2, 0x12010
	v_add3_u32 v0, v88, v0, s2
	v_and_b32_sdwa v88, v86, v186 dst_sel:DWORD dst_unused:UNUSED_PAD src0_sel:WORD_1 src1_sel:DWORD
	v_and_b32_sdwa v89, v84, v186 dst_sel:DWORD dst_unused:UNUSED_PAD src0_sel:WORD_1 src1_sel:DWORD
	v_add3_u32 v86, v86, v88, s31
	v_and_b32_sdwa v88, v87, v186 dst_sel:DWORD dst_unused:UNUSED_PAD src0_sel:WORD_1 src1_sel:DWORD
	v_add3_u32 v84, v84, v89, s31
	v_and_b32_sdwa v89, v85, v186 dst_sel:DWORD dst_unused:UNUSED_PAD src0_sel:WORD_1 src1_sel:DWORD
	v_add3_u32 v87, v87, v88, s31
	v_add3_u32 v85, v85, v89, s31
	v_and_b32_e32 v87, 0xffff0000, v87
	v_and_b32_e32 v88, 0xffff0000, v85
	v_or_b32_sdwa v85, v86, v87 dst_sel:DWORD dst_unused:UNUSED_PAD src0_sel:WORD_1 src1_sel:DWORD
	v_and_b32_sdwa v86, v82, v186 dst_sel:DWORD dst_unused:UNUSED_PAD src0_sel:WORD_1 src1_sel:DWORD
	v_and_b32_sdwa v87, v80, v186 dst_sel:DWORD dst_unused:UNUSED_PAD src0_sel:WORD_1 src1_sel:DWORD
	v_add3_u32 v80, v80, v87, s31
	v_add3_u32 v82, v82, v86, s31
	v_and_b32_sdwa v86, v83, v186 dst_sel:DWORD dst_unused:UNUSED_PAD src0_sel:WORD_1 src1_sel:DWORD
	v_and_b32_sdwa v87, v81, v186 dst_sel:DWORD dst_unused:UNUSED_PAD src0_sel:WORD_1 src1_sel:DWORD
	v_add3_u32 v83, v83, v86, s31
	v_add3_u32 v81, v81, v87, s31
	v_and_b32_e32 v83, 0xffff0000, v83
	v_and_b32_e32 v86, 0xffff0000, v81
	v_or_b32_sdwa v84, v84, v88 dst_sel:DWORD dst_unused:UNUSED_PAD src0_sel:WORD_1 src1_sel:DWORD
	v_or_b32_sdwa v81, v82, v83 dst_sel:DWORD dst_unused:UNUSED_PAD src0_sel:WORD_1 src1_sel:DWORD
	v_or_b32_sdwa v80, v80, v86 dst_sel:DWORD dst_unused:UNUSED_PAD src0_sel:WORD_1 src1_sel:DWORD
	ds_write2_b64 v0, v[84:85], v[80:81] offset1:4
	v_and_b32_sdwa v80, v78, v186 dst_sel:DWORD dst_unused:UNUSED_PAD src0_sel:WORD_1 src1_sel:DWORD
	v_and_b32_sdwa v81, v76, v186 dst_sel:DWORD dst_unused:UNUSED_PAD src0_sel:WORD_1 src1_sel:DWORD
	v_add3_u32 v78, v78, v80, s31
	v_and_b32_sdwa v80, v79, v186 dst_sel:DWORD dst_unused:UNUSED_PAD src0_sel:WORD_1 src1_sel:DWORD
	v_add3_u32 v76, v76, v81, s31
	v_and_b32_sdwa v81, v77, v186 dst_sel:DWORD dst_unused:UNUSED_PAD src0_sel:WORD_1 src1_sel:DWORD
	v_add3_u32 v79, v79, v80, s31
	v_add3_u32 v77, v77, v81, s31
	v_and_b32_e32 v79, 0xffff0000, v79
	v_and_b32_e32 v80, 0xffff0000, v77
	v_or_b32_sdwa v77, v78, v79 dst_sel:DWORD dst_unused:UNUSED_PAD src0_sel:WORD_1 src1_sel:DWORD
	v_and_b32_sdwa v78, v74, v186 dst_sel:DWORD dst_unused:UNUSED_PAD src0_sel:WORD_1 src1_sel:DWORD
	v_and_b32_sdwa v79, v72, v186 dst_sel:DWORD dst_unused:UNUSED_PAD src0_sel:WORD_1 src1_sel:DWORD
	v_add3_u32 v72, v72, v79, s31
	v_add3_u32 v74, v74, v78, s31
	v_and_b32_sdwa v78, v75, v186 dst_sel:DWORD dst_unused:UNUSED_PAD src0_sel:WORD_1 src1_sel:DWORD
	v_and_b32_sdwa v79, v73, v186 dst_sel:DWORD dst_unused:UNUSED_PAD src0_sel:WORD_1 src1_sel:DWORD
	v_add3_u32 v75, v75, v78, s31
	v_add3_u32 v73, v73, v79, s31
	v_and_b32_e32 v75, 0xffff0000, v75
	v_and_b32_e32 v78, 0xffff0000, v73
	v_or_b32_sdwa v76, v76, v80 dst_sel:DWORD dst_unused:UNUSED_PAD src0_sel:WORD_1 src1_sel:DWORD
	v_or_b32_sdwa v73, v74, v75 dst_sel:DWORD dst_unused:UNUSED_PAD src0_sel:WORD_1 src1_sel:DWORD
	v_or_b32_sdwa v72, v72, v78 dst_sel:DWORD dst_unused:UNUSED_PAD src0_sel:WORD_1 src1_sel:DWORD
	s_ashr_i32 s21, s20, 31
	ds_write2_b64 v0, v[76:77], v[72:73] offset0:8 offset1:12
	v_lshl_add_u64 v[72:73], v[106:107], 0, s[20:21]
	v_mov_b64_e32 v[74:75], s[10:11]
	v_mad_u64_u32 v[74:75], s[2:3], v72, s78, v[74:75]
	v_mov_b32_e32 v0, v75
	v_mad_u64_u32 v[72:73], s[2:3], v73, s78, v[0:1]
	v_mov_b32_e32 v75, v72
	v_lshl_add_u64 v[72:73], v[74:75], 0, s[80:81]
	v_mov_b32_e32 v109, v1
	v_lshl_add_u64 v[72:73], v[72:73], 0, v[108:109]
	s_mov_b64 s[2:3], 0x1500
	v_lshl_add_u64 v[76:77], v[72:73], 0, s[2:3]
	v_add_co_u32_e32 v72, vcc, s26, v72
	s_cmp_eq_u32 s36, 2
	s_nop 0
	v_addc_co_u32_e32 v73, vcc, 0, v73, vcc
	global_load_dwordx4 v[72:75], v[72:73], off offset:1280
	global_load_dwordx4 v[80:83], v[76:77], off offset:16
	s_cselect_b64 s[2:3], -1, 0
	s_cmp_lg_u32 s36, 1
	v_cndmask_b32_e64 v0, 0, -1.0, s[2:3]
	s_cselect_b64 vcc, -1, 0
	v_cndmask_b32_e32 v0, 1.0, v0, vcc
	v_mul_f32_e32 v109, v0, v200
	s_mov_b32 s2, 0xff61b1e6
	s_waitcnt vmcnt(1)
	ds_write_b16 v203, v72
	ds_write_b16_d16_hi v203, v72 offset:272
	ds_write_b16 v203, v73 offset:544
	ds_write_b16_d16_hi v203, v73 offset:816
	ds_write_b16 v203, v74 offset:1088
	ds_write_b16_d16_hi v203, v74 offset:1360
	ds_write_b16 v203, v75 offset:1632
	ds_write_b16_d16_hi v203, v75 offset:1904
	s_waitcnt vmcnt(0)
	ds_write_b16 v203, v80 offset:2176
	ds_write_b16_d16_hi v203, v80 offset:2448
	ds_write_b16 v203, v81 offset:2720
	ds_write_b16_d16_hi v203, v81 offset:2992
	ds_write_b16 v203, v82 offset:3264
	ds_write_b16_d16_hi v203, v82 offset:3536
	ds_write_b16 v203, v83 offset:3808
	ds_write_b16_d16_hi v203, v83 offset:4080
	s_waitcnt lgkmcnt(0)
	s_barrier
; DI void attn_tile(int j, int tile, LAS unsigned char* lds) {
;     ...
;         for (int g = 0; g < 4; ++g) {
;             asm volatile("" ::: "memory");
;             f32x4 s[8];
; #pragma unroll
;             for (int i = 0; i < 8; ++i) s[i] = (f32x4){0.f, 0.f, 0.f, 0.f};
;             mm16<8, 2>(Qs + g * 128 * 72 + wave * 16 * 72, 72, Ks, 72, s, fr, fq);
;             const int qi = wave * 16 + fr;
;             float mx = -3.0e38f;
; #pragma unroll
;             for (int nt = 0; nt < 8; ++nt)
; #pragma unroll
;                 for (int e = 0; e < 4; ++e) { const float tf = fmaf(sgnf, (float)(nt * 16 + e), basef);
;                     s[nt][e] += fminf(tf, 0.f) * 1.0e30f; mx = fmaxf(mx, s[nt][e]); }
;             mx = fmaxf(mx, __shfl_xor(mx, 16)); mx = fmaxf(mx, __shfl_xor(mx, 32));
	ds_read_b128 v[72:75], v201
	ds_read_b128 v[76:79], v204
	ds_read_b128 v[88:91], v204 offset:6912
	ds_read_b128 v[92:95], v204 offset:9216
	s_waitcnt lgkmcnt(0)
	v_mfma_f32_16x16x32_bf16 v[110:113], v[92:95], v[72:75], 0
	ds_read_b128 v[92:95], v204 offset:11520
	ds_read_b128 v[80:83], v204 offset:2304
	ds_read_b128 v[84:87], v204 offset:4608
	s_waitcnt lgkmcnt(2)
	v_mfma_f32_16x16x32_bf16 v[114:117], v[92:95], v[72:75], 0
	ds_read_b128 v[92:95], v204 offset:13824
	s_waitcnt lgkmcnt(0)
	v_mfma_f32_16x16x32_bf16 v[118:121], v[92:95], v[72:75], 0
	ds_read_b128 v[92:95], v204 offset:16128
	v_mfma_f32_16x16x32_bf16 v[76:79], v[76:79], v[72:75], 0
	v_mfma_f32_16x16x32_bf16 v[80:83], v[80:83], v[72:75], 0
	v_mfma_f32_16x16x32_bf16 v[84:87], v[84:87], v[72:75], 0
	v_mfma_f32_16x16x32_bf16 v[88:91], v[88:91], v[72:75], 0
	s_waitcnt lgkmcnt(0)
	v_mfma_f32_16x16x32_bf16 v[122:125], v[92:95], v[72:75], 0
	ds_read_b128 v[126:129], v201 offset:64
	ds_read_b128 v[72:75], v204 offset:64
	s_waitcnt lgkmcnt(0)
	v_mfma_f32_16x16x32_bf16 v[100:103], v[72:75], v[126:129], v[76:79]
	ds_read_b128 v[72:75], v204 offset:2368
	s_waitcnt lgkmcnt(0)
	v_mfma_f32_16x16x32_bf16 v[96:99], v[72:75], v[126:129], v[80:83]
	ds_read_b128 v[72:75], v204 offset:4672
	s_waitcnt lgkmcnt(0)
	v_mfma_f32_16x16x32_bf16 v[92:95], v[72:75], v[126:129], v[84:87]
	ds_read_b128 v[72:75], v204 offset:6976
	s_nop 1
	ds_read_b128 v[84:87], v204 offset:16192
	s_waitcnt lgkmcnt(1)
	v_mfma_f32_16x16x32_bf16 v[88:91], v[72:75], v[126:129], v[88:91]
	ds_read_b128 v[72:75], v204 offset:9280
	s_waitcnt lgkmcnt(0)
	v_mfma_f32_16x16x32_bf16 v[80:83], v[72:75], v[126:129], v[110:113]
	s_nop 2
	v_fma_f32 v111, 2.0, v0, v109
	v_min_f32_e32 v178, 0, v111
	v_fmamk_f32 v111, v0, 0x40400000, v109
	v_min_f32_e32 v180, 0, v111
	v_fmamk_f32 v111, v0, 0x41800000, v109
	v_min_f32_e32 v207, 0, v111
	v_fmamk_f32 v111, v0, 0x41880000, v109
	ds_read_b128 v[72:75], v204 offset:11584
	v_min_f32_e32 v208, 0, v111
	v_fmamk_f32 v111, v0, 0x41900000, v109
	v_min_f32_e32 v209, 0, v111
	v_fmamk_f32 v111, v0, 0x41980000, v109
	v_min_f32_e32 v210, 0, v111
	v_fmamk_f32 v111, v0, 0x42000000, v109
	v_min_f32_e32 v211, 0, v111
	v_fmamk_f32 v111, v0, 0x42040000, v109
	v_min_f32_e32 v212, 0, v111
	v_fmamk_f32 v111, v0, 0x42080000, v109
	v_min_f32_e32 v213, 0, v111
	v_fmamk_f32 v111, v0, 0x420c0000, v109
	v_min_f32_e32 v214, 0, v111
	v_fmamk_f32 v111, v0, 0x42400000, v109
	v_min_f32_e32 v215, 0, v111
	v_fmamk_f32 v111, v0, 0x42440000, v109
	v_min_f32_e32 v216, 0, v111
	v_fmamk_f32 v111, v0, 0x42480000, v109
	s_waitcnt lgkmcnt(0)
	v_mfma_f32_16x16x32_bf16 v[76:79], v[72:75], v[126:129], v[114:117]
	ds_read_b128 v[72:75], v204 offset:13888
	v_min_f32_e32 v217, 0, v111
	v_fmamk_f32 v111, v0, 0x424c0000, v109
	v_min_f32_e32 v218, 0, v111
	v_fmamk_f32 v111, v0, 0x42800000, v109
	v_min_f32_e32 v219, 0, v111
	v_fmamk_f32 v111, v0, 0x42820000, v109
	v_fma_f32 v110, 0, v0, v109
	v_min_f32_e32 v220, 0, v111
	v_fmamk_f32 v111, v0, 0x42840000, v109
	v_min_f32_e32 v174, 0, v110
	v_fma_f32 v110, v0, v200, v0
	v_min_f32_e32 v221, 0, v111
	v_fmamk_f32 v111, v0, 0x42860000, v109
	v_min_f32_e32 v176, 0, v110
	v_min_f32_e32 v222, 0, v111
	v_fmamk_f32 v111, v0, 0x42a00000, v109
	v_fmamk_f32 v100, v174, 0x7149f2ca, v100
	v_fmamk_f32 v101, v176, 0x7149f2ca, v101
	v_min_f32_e32 v223, 0, v111
	v_max3_f32 v110, v100, s2, v101
	v_fmamk_f32 v102, v178, 0x7149f2ca, v102
	v_fmac_f32_e32 v103, 0x7149f2ca, v180
	v_fmamk_f32 v111, v223, 0x7149f2ca, v76
	v_fmamk_f32 v76, v0, 0x42a20000, v109
	v_max3_f32 v110, v110, v102, v103
	v_fmamk_f32 v96, v207, 0x7149f2ca, v96
	v_fmamk_f32 v97, v208, 0x7149f2ca, v97
	v_min_f32_e32 v224, 0, v76
	s_waitcnt lgkmcnt(0)
	v_mfma_f32_16x16x32_bf16 v[72:75], v[72:75], v[126:129], v[118:121]
	v_max3_f32 v110, v110, v96, v97
	v_fmamk_f32 v98, v209, 0x7149f2ca, v98
	v_fmac_f32_e32 v99, 0x7149f2ca, v210
	v_fmamk_f32 v112, v224, 0x7149f2ca, v77
	v_fmamk_f32 v77, v0, 0x42a40000, v109
	v_max3_f32 v110, v110, v98, v99
	v_fmamk_f32 v92, v211, 0x7149f2ca, v92
	v_fmamk_f32 v93, v212, 0x7149f2ca, v93
	v_min_f32_e32 v225, 0, v77
	v_fmamk_f32 v77, v0, 0x42a60000, v109
	v_max3_f32 v110, v110, v92, v93
	v_fmamk_f32 v94, v213, 0x7149f2ca, v94
	v_fmac_f32_e32 v95, 0x7149f2ca, v214
	v_min_f32_e32 v226, 0, v77
	v_fmamk_f32 v77, v0, 0x42c00000, v109
	v_max3_f32 v110, v110, v94, v95
	v_fmamk_f32 v88, v215, 0x7149f2ca, v88
	v_fmamk_f32 v89, v216, 0x7149f2ca, v89
	v_min_f32_e32 v227, 0, v77
	v_max3_f32 v110, v110, v88, v89
	v_fmamk_f32 v90, v217, 0x7149f2ca, v90
	v_fmac_f32_e32 v91, 0x7149f2ca, v218
	v_fmamk_f32 v113, v227, 0x7149f2ca, v72
	v_fmamk_f32 v72, v0, 0x42c20000, v109
	v_max3_f32 v110, v110, v90, v91
	v_fmamk_f32 v80, v219, 0x7149f2ca, v80
	v_fmamk_f32 v81, v220, 0x7149f2ca, v81
	v_min_f32_e32 v228, 0, v72
	v_max3_f32 v110, v110, v80, v81
	v_fmamk_f32 v82, v221, 0x7149f2ca, v82
	v_fmac_f32_e32 v83, 0x7149f2ca, v222
	v_fmamk_f32 v114, v228, 0x7149f2ca, v73
	v_fmamk_f32 v73, v0, 0x42c40000, v109
	v_mfma_f32_16x16x32_bf16 v[84:87], v[84:87], v[126:129], v[122:125]
	v_max3_f32 v110, v110, v82, v83
	v_min_f32_e32 v229, 0, v73
	v_fmamk_f32 v73, v0, 0x42c60000, v109
	v_max3_f32 v76, v110, v111, v112
	v_fmamk_f32 v78, v225, 0x7149f2ca, v78
	v_fmac_f32_e32 v79, 0x7149f2ca, v226
	v_min_f32_e32 v230, 0, v73
	v_fmamk_f32 v73, v0, 0x42e00000, v109
	v_max3_f32 v76, v76, v78, v79
	v_min_f32_e32 v231, 0, v73
	v_fmamk_f32 v73, v0, 0x42e20000, v109
	v_max3_f32 v72, v76, v113, v114
	v_fmamk_f32 v74, v229, 0x7149f2ca, v74
	v_fmac_f32_e32 v75, 0x7149f2ca, v230
	v_min_f32_e32 v232, 0, v73
	v_fmamk_f32 v73, v0, 0x42e40000, v109
	v_fmac_f32_e32 v109, 0x42e60000, v0
	v_max3_f32 v72, v72, v74, v75
	v_fmamk_f32 v84, v231, 0x7149f2ca, v84
	v_fmamk_f32 v85, v232, 0x7149f2ca, v85
	v_min_f32_e32 v233, 0, v73
	v_min_f32_e32 v234, 0, v109
	v_max3_f32 v72, v72, v84, v85
	v_fmamk_f32 v86, v233, 0x7149f2ca, v86
	v_fmac_f32_e32 v87, 0x7149f2ca, v234
	v_and_b32_e32 v73, 64, v187
	v_max3_f32 v0, v72, v86, v87
	v_xor_b32_e32 v72, 16, v187
	v_add_u32_e32 v73, 64, v73
	v_cmp_lt_i32_e32 vcc, v72, v73
	s_nop 1
	v_cndmask_b32_e32 v72, v187, v72, vcc
	v_lshlrev_b32_e32 v109, 2, v72
	ds_bpermute_b32 v72, v109, v0
	s_waitcnt lgkmcnt(0)
; #define LAS __attribute__((address_space(3)))
; DI unsigned pk2(float lo, float hi) { return f2bf(lo) | (f2bf(hi) << 16); }
; DI void attn_tile(int j, int tile, LAS unsigned char* lds) {
;     ...
;             mx = fmaxf(mx, __shfl_xor(mx, 16)); mx = fmaxf(mx, __shfl_xor(mx, 32));
;             const float mn = fmaxf(mr[g], mx); const float alpha = __expf(mr[g] - mn);
;             float rs = 0.f;
; #pragma unroll
;             for (int nt = 0; nt < 8; ++nt) { float o[4];
; #pragma unroll
;                 for (int e = 0; e < 4; ++e) { o[e] = __expf(s[nt][e] - mn); rs += o[e]; }
;                 u32x2 w2; w2.x = pk2(o[0], o[1]); w2.y = pk2(o[2], o[3]);
;                 *(LAS u32x2*)(Ps + qi * 136 + nt * 16 + fq * 4) = w2; }
	v_max_f32_e32 v72, v72, v72
	v_max_f32_e32 v0, v0, v72
	v_xor_b32_e32 v72, 32, v187
	v_cmp_lt_i32_e32 vcc, v72, v73
	s_nop 1
	v_cndmask_b32_e32 v72, v187, v72, vcc
	v_lshlrev_b32_e32 v139, 2, v72
	ds_bpermute_b32 v72, v139, v0
	s_waitcnt lgkmcnt(0)
	v_max3_f32 v110, v68, v0, v72
	v_sub_f32_e32 v0, v68, v110
	v_sub_f32_e32 v68, v100, v110
	v_mul_f32_e32 v68, 0x3fb8aa3b, v68
	v_exp_f32_e32 v173, v68
	v_sub_f32_e32 v68, v101, v110
	v_mul_f32_e32 v68, 0x3fb8aa3b, v68
	v_exp_f32_e32 v171, v68
	v_sub_f32_e32 v68, v102, v110
	v_mul_f32_e32 v68, 0x3fb8aa3b, v68
	v_exp_f32_e32 v151, v68
	v_sub_f32_e32 v68, v103, v110
	v_mul_f32_e32 v68, 0x3fb8aa3b, v68
	v_exp_f32_e32 v153, v68
	v_and_b32_sdwa v68, v151, v186 dst_sel:DWORD dst_unused:UNUSED_PAD src0_sel:WORD_1 src1_sel:DWORD
	v_add3_u32 v68, v151, v68, s31
	v_and_b32_sdwa v76, v171, v186 dst_sel:DWORD dst_unused:UNUSED_PAD src0_sel:WORD_1 src1_sel:DWORD
	v_and_b32_sdwa v73, v153, v186 dst_sel:DWORD dst_unused:UNUSED_PAD src0_sel:WORD_1 src1_sel:DWORD
	v_add3_u32 v73, v153, v73, s31
	v_and_b32_e32 v73, 0xffff0000, v73
	v_or_b32_sdwa v73, v73, v68 dst_sel:DWORD dst_unused:UNUSED_PAD src0_sel:DWORD src1_sel:WORD_1
	v_sub_f32_e32 v68, v96, v110
	v_mul_f32_e32 v68, 0x3fb8aa3b, v68
	v_exp_f32_e32 v155, v68
	v_sub_f32_e32 v68, v97, v110
	v_mul_f32_e32 v68, 0x3fb8aa3b, v68
	v_exp_f32_e32 v157, v68
	v_sub_f32_e32 v68, v98, v110
	v_mul_f32_e32 v68, 0x3fb8aa3b, v68
	v_exp_f32_e32 v159, v68
	v_sub_f32_e32 v68, v99, v110
	v_mul_f32_e32 v68, 0x3fb8aa3b, v68
	v_exp_f32_e32 v161, v68
	v_and_b32_sdwa v68, v159, v186 dst_sel:DWORD dst_unused:UNUSED_PAD src0_sel:WORD_1 src1_sel:DWORD
	v_add3_u32 v68, v159, v68, s31
	v_and_b32_sdwa v72, v173, v186 dst_sel:DWORD dst_unused:UNUSED_PAD src0_sel:WORD_1 src1_sel:DWORD
	v_and_b32_sdwa v77, v161, v186 dst_sel:DWORD dst_unused:UNUSED_PAD src0_sel:WORD_1 src1_sel:DWORD
	v_add3_u32 v77, v161, v77, s31
	v_and_b32_e32 v77, 0xffff0000, v77
	v_or_b32_sdwa v77, v77, v68 dst_sel:DWORD dst_unused:UNUSED_PAD src0_sel:DWORD src1_sel:WORD_1
	v_sub_f32_e32 v68, v92, v110
	v_mul_f32_e32 v68, 0x3fb8aa3b, v68
	v_exp_f32_e32 v163, v68
	v_sub_f32_e32 v68, v93, v110
	v_mul_f32_e32 v68, 0x3fb8aa3b, v68
	v_exp_f32_e32 v165, v68
	v_sub_f32_e32 v68, v94, v110
	v_mul_f32_e32 v68, 0x3fb8aa3b, v68
	v_exp_f32_e32 v167, v68
	v_sub_f32_e32 v68, v95, v110
	v_add3_u32 v76, v171, v76, s31
	v_mul_f32_e32 v68, 0x3fb8aa3b, v68
	v_add3_u32 v72, v173, v72, s31
	v_and_b32_e32 v76, 0xffff0000, v76
	v_and_b32_sdwa v96, v157, v186 dst_sel:DWORD dst_unused:UNUSED_PAD src0_sel:WORD_1 src1_sel:DWORD
	v_exp_f32_e32 v169, v68
	v_or_b32_sdwa v72, v76, v72 dst_sel:DWORD dst_unused:UNUSED_PAD src0_sel:DWORD src1_sel:WORD_1
	v_and_b32_sdwa v76, v155, v186 dst_sel:DWORD dst_unused:UNUSED_PAD src0_sel:WORD_1 src1_sel:DWORD
	v_add3_u32 v96, v157, v96, s31
	v_add3_u32 v76, v155, v76, s31
	v_and_b32_e32 v96, 0xffff0000, v96
	v_or_b32_sdwa v76, v96, v76 dst_sel:DWORD dst_unused:UNUSED_PAD src0_sel:DWORD src1_sel:WORD_1
	ds_write2_b64 v205, v[72:73], v[76:77] offset1:4
	v_and_b32_sdwa v73, v169, v186 dst_sel:DWORD dst_unused:UNUSED_PAD src0_sel:WORD_1 src1_sel:DWORD
	v_and_b32_sdwa v68, v167, v186 dst_sel:DWORD dst_unused:UNUSED_PAD src0_sel:WORD_1 src1_sel:DWORD
	v_add3_u32 v73, v169, v73, s31
	v_add3_u32 v68, v167, v68, s31
	v_and_b32_e32 v73, 0xffff0000, v73
	v_or_b32_sdwa v73, v73, v68 dst_sel:DWORD dst_unused:UNUSED_PAD src0_sel:DWORD src1_sel:WORD_1
	v_sub_f32_e32 v68, v88, v110
	v_mul_f32_e32 v68, 0x3fb8aa3b, v68
	v_exp_f32_e32 v149, v68
	v_sub_f32_e32 v68, v89, v110
	v_mul_f32_e32 v68, 0x3fb8aa3b, v68
	v_exp_f32_e32 v129, v68
	v_sub_f32_e32 v68, v90, v110
	v_mul_f32_e32 v68, 0x3fb8aa3b, v68
	v_exp_f32_e32 v131, v68
	v_sub_f32_e32 v68, v91, v110
	v_mul_f32_e32 v68, 0x3fb8aa3b, v68
	v_exp_f32_e32 v133, v68
	v_and_b32_sdwa v68, v131, v186 dst_sel:DWORD dst_unused:UNUSED_PAD src0_sel:WORD_1 src1_sel:DWORD
	v_add3_u32 v68, v131, v68, s31
	v_and_b32_sdwa v76, v165, v186 dst_sel:DWORD dst_unused:UNUSED_PAD src0_sel:WORD_1 src1_sel:DWORD
	v_and_b32_sdwa v77, v133, v186 dst_sel:DWORD dst_unused:UNUSED_PAD src0_sel:WORD_1 src1_sel:DWORD
	v_add3_u32 v77, v133, v77, s31
	v_and_b32_e32 v77, 0xffff0000, v77
	v_or_b32_sdwa v77, v77, v68 dst_sel:DWORD dst_unused:UNUSED_PAD src0_sel:DWORD src1_sel:WORD_1
	v_sub_f32_e32 v68, v80, v110
	v_mul_f32_e32 v68, 0x3fb8aa3b, v68
	v_exp_f32_e32 v135, v68
	v_sub_f32_e32 v68, v81, v110
	v_mul_f32_e32 v68, 0x3fb8aa3b, v68
	v_exp_f32_e32 v137, v68
	v_sub_f32_e32 v68, v82, v110
	v_mul_f32_e32 v68, 0x3fb8aa3b, v68
	v_exp_f32_e32 v145, v68
	v_sub_f32_e32 v68, v83, v110
	v_and_b32_sdwa v72, v163, v186 dst_sel:DWORD dst_unused:UNUSED_PAD src0_sel:WORD_1 src1_sel:DWORD
	v_add3_u32 v76, v165, v76, s31
	v_mul_f32_e32 v68, 0x3fb8aa3b, v68
	v_add3_u32 v72, v163, v72, s31
	v_and_b32_e32 v76, 0xffff0000, v76
	v_and_b32_sdwa v88, v129, v186 dst_sel:DWORD dst_unused:UNUSED_PAD src0_sel:WORD_1 src1_sel:DWORD
	v_exp_f32_e32 v147, v68
	v_or_b32_sdwa v72, v76, v72 dst_sel:DWORD dst_unused:UNUSED_PAD src0_sel:DWORD src1_sel:WORD_1
	v_and_b32_sdwa v76, v149, v186 dst_sel:DWORD dst_unused:UNUSED_PAD src0_sel:WORD_1 src1_sel:DWORD
	v_add3_u32 v88, v129, v88, s31
	v_add3_u32 v76, v149, v76, s31
	v_and_b32_e32 v88, 0xffff0000, v88
	v_or_b32_sdwa v76, v88, v76 dst_sel:DWORD dst_unused:UNUSED_PAD src0_sel:DWORD src1_sel:WORD_1
	ds_write2_b64 v205, v[72:73], v[76:77] offset0:8 offset1:12
	v_and_b32_sdwa v73, v147, v186 dst_sel:DWORD dst_unused:UNUSED_PAD src0_sel:WORD_1 src1_sel:DWORD
	v_and_b32_sdwa v68, v145, v186 dst_sel:DWORD dst_unused:UNUSED_PAD src0_sel:WORD_1 src1_sel:DWORD
	v_add3_u32 v73, v147, v73, s31
; #define LAS __attribute__((address_space(3)))
; DI unsigned pk2(float lo, float hi) { return f2bf(lo) | (f2bf(hi) << 16); }
; DI void attn_tile(int j, int tile, LAS unsigned char* lds) {
;     ...
;             for (int nt = 0; nt < 8; ++nt) { float o[4];
; #pragma unroll
;                 for (int e = 0; e < 4; ++e) { o[e] = __expf(s[nt][e] - mn); rs += o[e]; }
;                 u32x2 w2; w2.x = pk2(o[0], o[1]); w2.y = pk2(o[2], o[3]);
;                 *(LAS u32x2*)(Ps + qi * 136 + nt * 16 + fq * 4) = w2; }
;             rs += __shfl_xor(rs, 16); rs += __shfl_xor(rs, 32);
;             lr[g] = lr[g] * alpha + rs; mr[g] = mn;
; #pragma unroll
;             for (int i = 0; i < 4; ++i) O[g][i] *= alpha;
;             mm16<4, 4>(Ps + wave * 16 * 136, 136, VTs, 136, O[g], fr, fq);
	v_add3_u32 v68, v145, v68, s31
	v_and_b32_e32 v73, 0xffff0000, v73
	v_or_b32_sdwa v73, v73, v68 dst_sel:DWORD dst_unused:UNUSED_PAD src0_sel:DWORD src1_sel:WORD_1
	v_sub_f32_e32 v68, v111, v110
	v_mul_f32_e32 v68, 0x3fb8aa3b, v68
	v_exp_f32_e32 v123, v68
	v_sub_f32_e32 v68, v112, v110
	v_mul_f32_e32 v68, 0x3fb8aa3b, v68
	v_exp_f32_e32 v121, v68
	v_sub_f32_e32 v68, v78, v110
	v_mul_f32_e32 v68, 0x3fb8aa3b, v68
	v_exp_f32_e32 v127, v68
	v_sub_f32_e32 v68, v79, v110
	v_mul_f32_e32 v68, 0x3fb8aa3b, v68
	v_exp_f32_e32 v125, v68
	v_and_b32_sdwa v68, v127, v186 dst_sel:DWORD dst_unused:UNUSED_PAD src0_sel:WORD_1 src1_sel:DWORD
	v_add3_u32 v68, v127, v68, s31
	v_and_b32_sdwa v76, v137, v186 dst_sel:DWORD dst_unused:UNUSED_PAD src0_sel:WORD_1 src1_sel:DWORD
	v_and_b32_sdwa v77, v125, v186 dst_sel:DWORD dst_unused:UNUSED_PAD src0_sel:WORD_1 src1_sel:DWORD
	v_add3_u32 v77, v125, v77, s31
	v_and_b32_e32 v77, 0xffff0000, v77
	v_or_b32_sdwa v77, v77, v68 dst_sel:DWORD dst_unused:UNUSED_PAD src0_sel:DWORD src1_sel:WORD_1
	v_sub_f32_e32 v68, v113, v110
	v_mul_f32_e32 v68, 0x3fb8aa3b, v68
	v_exp_f32_e32 v97, v68
	v_sub_f32_e32 v68, v114, v110
	v_mul_f32_e32 v68, 0x3fb8aa3b, v68
	v_exp_f32_e32 v99, v68
	v_sub_f32_e32 v68, v74, v110
	v_mul_f32_e32 v68, 0x3fb8aa3b, v68
	v_exp_f32_e32 v101, v68
	v_sub_f32_e32 v68, v75, v110
	v_and_b32_sdwa v72, v135, v186 dst_sel:DWORD dst_unused:UNUSED_PAD src0_sel:WORD_1 src1_sel:DWORD
	v_add3_u32 v76, v137, v76, s31
	v_mul_f32_e32 v68, 0x3fb8aa3b, v68
	v_add3_u32 v72, v135, v72, s31
	v_and_b32_e32 v76, 0xffff0000, v76
	v_and_b32_sdwa v78, v121, v186 dst_sel:DWORD dst_unused:UNUSED_PAD src0_sel:WORD_1 src1_sel:DWORD
	v_exp_f32_e32 v103, v68
	v_or_b32_sdwa v72, v76, v72 dst_sel:DWORD dst_unused:UNUSED_PAD src0_sel:DWORD src1_sel:WORD_1
	v_and_b32_sdwa v76, v123, v186 dst_sel:DWORD dst_unused:UNUSED_PAD src0_sel:WORD_1 src1_sel:DWORD
	v_add3_u32 v78, v121, v78, s31
	v_add3_u32 v76, v123, v76, s31
	v_and_b32_e32 v78, 0xffff0000, v78
	v_or_b32_sdwa v76, v78, v76 dst_sel:DWORD dst_unused:UNUSED_PAD src0_sel:DWORD src1_sel:WORD_1
	ds_write2_b64 v205, v[72:73], v[76:77] offset0:16 offset1:20
	v_and_b32_sdwa v73, v103, v186 dst_sel:DWORD dst_unused:UNUSED_PAD src0_sel:WORD_1 src1_sel:DWORD
	v_and_b32_sdwa v68, v101, v186 dst_sel:DWORD dst_unused:UNUSED_PAD src0_sel:WORD_1 src1_sel:DWORD
	v_add3_u32 v73, v103, v73, s31
	v_add3_u32 v68, v101, v68, s31
	v_and_b32_e32 v73, 0xffff0000, v73
	v_or_b32_sdwa v73, v73, v68 dst_sel:DWORD dst_unused:UNUSED_PAD src0_sel:DWORD src1_sel:WORD_1
	v_sub_f32_e32 v68, v84, v110
	v_mul_f32_e32 v68, 0x3fb8aa3b, v68
	v_exp_f32_e32 v113, v68
	v_sub_f32_e32 v68, v85, v110
	v_mul_f32_e32 v68, 0x3fb8aa3b, v68
	v_exp_f32_e32 v115, v68
	v_sub_f32_e32 v68, v86, v110
	v_mul_f32_e32 v68, 0x3fb8aa3b, v68
	v_exp_f32_e32 v117, v68
	v_sub_f32_e32 v68, v87, v110
	v_mul_f32_e32 v68, 0x3fb8aa3b, v68
	v_exp_f32_e32 v119, v68
	v_and_b32_sdwa v74, v99, v186 dst_sel:DWORD dst_unused:UNUSED_PAD src0_sel:WORD_1 src1_sel:DWORD
	v_and_b32_sdwa v72, v97, v186 dst_sel:DWORD dst_unused:UNUSED_PAD src0_sel:WORD_1 src1_sel:DWORD
	v_add3_u32 v74, v99, v74, s31
	v_add3_u32 v72, v97, v72, s31
	v_and_b32_e32 v74, 0xffff0000, v74
	v_and_b32_sdwa v75, v119, v186 dst_sel:DWORD dst_unused:UNUSED_PAD src0_sel:WORD_1 src1_sel:DWORD
	v_and_b32_sdwa v76, v115, v186 dst_sel:DWORD dst_unused:UNUSED_PAD src0_sel:WORD_1 src1_sel:DWORD
	v_or_b32_sdwa v72, v74, v72 dst_sel:DWORD dst_unused:UNUSED_PAD src0_sel:DWORD src1_sel:WORD_1
	v_and_b32_sdwa v68, v117, v186 dst_sel:DWORD dst_unused:UNUSED_PAD src0_sel:WORD_1 src1_sel:DWORD
	v_and_b32_sdwa v74, v113, v186 dst_sel:DWORD dst_unused:UNUSED_PAD src0_sel:WORD_1 src1_sel:DWORD
	v_add3_u32 v75, v119, v75, s31
	v_add3_u32 v76, v115, v76, s31
	v_add3_u32 v74, v113, v74, s31
	v_add3_u32 v68, v117, v68, s31
	v_and_b32_e32 v75, 0xffff0000, v75
	v_and_b32_e32 v76, 0xffff0000, v76
	v_or_b32_sdwa v75, v75, v68 dst_sel:DWORD dst_unused:UNUSED_PAD src0_sel:DWORD src1_sel:WORD_1
	v_or_b32_sdwa v74, v76, v74 dst_sel:DWORD dst_unused:UNUSED_PAD src0_sel:DWORD src1_sel:WORD_1
	v_mul_f32_e32 v0, 0x3fb8aa3b, v0
	ds_write2_b64 v205, v[72:73], v[74:75] offset0:24 offset1:28
	v_exp_f32_e32 v0, v0
	ds_read_b128 v[72:75], v202
	ds_read_b128 v[76:79], v206
	v_pk_mul_f32 v[66:67], v[66:67], v[0:1] op_sel_hi:[1,0]
	v_pk_mul_f32 v[64:65], v[64:65], v[0:1] op_sel_hi:[1,0]
	v_pk_mul_f32 v[62:63], v[62:63], v[0:1] op_sel_hi:[1,0]
	v_pk_mul_f32 v[60:61], v[60:61], v[0:1] op_sel_hi:[1,0]
	s_waitcnt lgkmcnt(0)
	v_mfma_f32_16x16x32_bf16 v[64:67], v[76:79], v[72:75], v[64:67]
	ds_read_b128 v[76:79], v206 offset:4352
	v_pk_mul_f32 v[58:59], v[58:59], v[0:1] op_sel_hi:[1,0]
	v_pk_mul_f32 v[56:57], v[56:57], v[0:1] op_sel_hi:[1,0]
	s_waitcnt lgkmcnt(0)
	v_mfma_f32_16x16x32_bf16 v[60:63], v[76:79], v[72:75], v[60:63]
	ds_read_b128 v[76:79], v206 offset:8704
	v_pk_mul_f32 v[54:55], v[54:55], v[0:1] op_sel_hi:[1,0]
	v_pk_mul_f32 v[52:53], v[52:53], v[0:1] op_sel_hi:[1,0]
	s_waitcnt lgkmcnt(0)
	v_mfma_f32_16x16x32_bf16 v[56:59], v[76:79], v[72:75], v[56:59]
	ds_read_b128 v[76:79], v206 offset:13056
	s_waitcnt lgkmcnt(0)
	v_mfma_f32_16x16x32_bf16 v[52:55], v[76:79], v[72:75], v[52:55]
	ds_read_b128 v[72:75], v202 offset:64
	ds_read_b128 v[76:79], v206 offset:64
	s_waitcnt lgkmcnt(0)
	v_mfma_f32_16x16x32_bf16 v[64:67], v[76:79], v[72:75], v[64:67]
	ds_read_b128 v[76:79], v206 offset:4416
	s_waitcnt lgkmcnt(0)
	v_mfma_f32_16x16x32_bf16 v[60:63], v[76:79], v[72:75], v[60:63]
	ds_read_b128 v[76:79], v206 offset:8768
	s_waitcnt lgkmcnt(0)
	v_mfma_f32_16x16x32_bf16 v[56:59], v[76:79], v[72:75], v[56:59]
	ds_read_b128 v[76:79], v206 offset:13120
	s_waitcnt lgkmcnt(0)
; DI void attn_tile(int j, int tile, LAS unsigned char* lds) {
;     ...
;             mm16<8, 2>(Qs + g * 128 * 72 + wave * 16 * 72, 72, Ks, 72, s, fr, fq);
;             const int qi = wave * 16 + fr;
;             float mx = -3.0e38f;
; #pragma unroll
;             for (int nt = 0; nt < 8; ++nt)
; #pragma unroll
;                 for (int e = 0; e < 4; ++e) { const float tf = fmaf(sgnf, (float)(nt * 16 + e), basef);
;                     s[nt][e] += fminf(tf, 0.f) * 1.0e30f; mx = fmaxf(mx, s[nt][e]); }
;             mx = fmaxf(mx, __shfl_xor(mx, 16)); mx = fmaxf(mx, __shfl_xor(mx, 32));
;     ...
;             mm16<4, 4>(Ps + wave * 16 * 136, 136, VTs, 136, O[g], fr, fq);
	v_mfma_f32_16x16x32_bf16 v[52:55], v[76:79], v[72:75], v[52:55]
	ds_read_b128 v[72:75], v202 offset:128
	ds_read_b128 v[76:79], v206 offset:128
	s_waitcnt lgkmcnt(0)
	v_mfma_f32_16x16x32_bf16 v[64:67], v[76:79], v[72:75], v[64:67]
	ds_read_b128 v[76:79], v206 offset:4480
	s_waitcnt lgkmcnt(0)
	v_mfma_f32_16x16x32_bf16 v[60:63], v[76:79], v[72:75], v[60:63]
	ds_read_b128 v[76:79], v206 offset:8832
	s_waitcnt lgkmcnt(0)
	v_mfma_f32_16x16x32_bf16 v[56:59], v[76:79], v[72:75], v[56:59]
	ds_read_b128 v[76:79], v206 offset:13184
	s_waitcnt lgkmcnt(0)
	v_mfma_f32_16x16x32_bf16 v[52:55], v[76:79], v[72:75], v[52:55]
	ds_read_b128 v[72:75], v202 offset:192
	ds_read_b128 v[76:79], v206 offset:192
	s_waitcnt lgkmcnt(0)
	v_mfma_f32_16x16x32_bf16 v[64:67], v[76:79], v[72:75], v[64:67]
	ds_read_b128 v[76:79], v206 offset:4544
	s_waitcnt lgkmcnt(0)
	v_mfma_f32_16x16x32_bf16 v[60:63], v[76:79], v[72:75], v[60:63]
	ds_read_b128 v[76:79], v206 offset:8896
	s_waitcnt lgkmcnt(0)
	v_mfma_f32_16x16x32_bf16 v[56:59], v[76:79], v[72:75], v[56:59]
	ds_read_b128 v[76:79], v206 offset:13248
	s_waitcnt lgkmcnt(0)
	v_mfma_f32_16x16x32_bf16 v[52:55], v[76:79], v[72:75], v[52:55]
	ds_read_b128 v[72:75], v201 offset:18432
	ds_read_b128 v[76:79], v204
	ds_read_b128 v[88:91], v204 offset:6912
	ds_read_b128 v[92:95], v204 offset:9216
	s_waitcnt lgkmcnt(0)
	v_mfma_f32_16x16x32_bf16 v[236:239], v[92:95], v[72:75], 0
	ds_read_b128 v[92:95], v204 offset:11520
	ds_read_b128 v[80:83], v204 offset:2304
	ds_read_b128 v[84:87], v204 offset:4608
	s_waitcnt lgkmcnt(2)
	v_mfma_f32_16x16x32_bf16 v[240:243], v[92:95], v[72:75], 0
	ds_read_b128 v[92:95], v204 offset:13824
	s_waitcnt lgkmcnt(0)
	v_mfma_f32_16x16x32_bf16 v[244:247], v[92:95], v[72:75], 0
	ds_read_b128 v[92:95], v204 offset:16128
	v_mfma_f32_16x16x32_bf16 v[76:79], v[76:79], v[72:75], 0
	v_mfma_f32_16x16x32_bf16 v[80:83], v[80:83], v[72:75], 0
	v_mfma_f32_16x16x32_bf16 v[84:87], v[84:87], v[72:75], 0
	v_mfma_f32_16x16x32_bf16 v[88:91], v[88:91], v[72:75], 0
	s_waitcnt lgkmcnt(0)
	v_mfma_f32_16x16x32_bf16 v[248:251], v[92:95], v[72:75], 0
	ds_read_b128 v[140:143], v201 offset:18496
	ds_read_b128 v[72:75], v204 offset:64
	s_waitcnt lgkmcnt(0)
	v_mfma_f32_16x16x32_bf16 v[192:195], v[72:75], v[140:143], v[76:79]
	ds_read_b128 v[72:75], v204 offset:2368
	s_nop 1
	ds_read_b128 v[76:79], v204 offset:16192
	s_waitcnt lgkmcnt(1)
	v_mfma_f32_16x16x32_bf16 v[188:191], v[72:75], v[140:143], v[80:83]
	ds_read_b128 v[72:75], v204 offset:4672
	s_nop 0
	v_fmamk_f32 v68, v174, 0x7149f2ca, v192
	v_fmamk_f32 v96, v176, 0x7149f2ca, v193
	s_waitcnt lgkmcnt(0)
	v_mfma_f32_16x16x32_bf16 v[92:95], v[72:75], v[140:143], v[84:87]
	ds_read_b128 v[72:75], v204 offset:6976
	v_max3_f32 v98, v68, s2, v96
	v_fmamk_f32 v100, v178, 0x7149f2ca, v194
	s_waitcnt lgkmcnt(0)
	v_mfma_f32_16x16x32_bf16 v[88:91], v[72:75], v[140:143], v[88:91]
	ds_read_b128 v[72:75], v204 offset:9280
	v_fmac_f32_e32 v195, 0x7149f2ca, v180
	v_max3_f32 v98, v98, v100, v195
	s_waitcnt lgkmcnt(0)
	v_mfma_f32_16x16x32_bf16 v[84:87], v[72:75], v[140:143], v[236:239]
	ds_read_b128 v[72:75], v204 offset:11584
	v_fmamk_f32 v102, v207, 0x7149f2ca, v188
	v_fmamk_f32 v112, v208, 0x7149f2ca, v189
	s_waitcnt lgkmcnt(0)
	v_mfma_f32_16x16x32_bf16 v[80:83], v[72:75], v[140:143], v[240:243]
	ds_read_b128 v[72:75], v204 offset:13888
	v_max3_f32 v98, v98, v102, v112
	v_fmamk_f32 v114, v209, 0x7149f2ca, v190
	v_fmac_f32_e32 v191, 0x7149f2ca, v210
	v_max3_f32 v98, v98, v114, v191
	v_fmamk_f32 v92, v211, 0x7149f2ca, v92
	v_fmamk_f32 v93, v212, 0x7149f2ca, v93
	v_max3_f32 v98, v98, v92, v93
	v_fmamk_f32 v94, v213, 0x7149f2ca, v94
	v_fmac_f32_e32 v95, 0x7149f2ca, v214
	v_max3_f32 v98, v98, v94, v95
	v_fmamk_f32 v88, v215, 0x7149f2ca, v88
	v_fmamk_f32 v89, v216, 0x7149f2ca, v89
	v_max3_f32 v98, v98, v88, v89
	v_fmamk_f32 v90, v217, 0x7149f2ca, v90
	v_fmac_f32_e32 v91, 0x7149f2ca, v218
	s_waitcnt lgkmcnt(0)
	v_mfma_f32_16x16x32_bf16 v[72:75], v[72:75], v[140:143], v[244:247]
	v_max3_f32 v98, v98, v90, v91
	v_fmamk_f32 v84, v219, 0x7149f2ca, v84
	v_fmamk_f32 v85, v220, 0x7149f2ca, v85
	v_max3_f32 v98, v98, v84, v85
	v_fmamk_f32 v86, v221, 0x7149f2ca, v86
	v_fmac_f32_e32 v87, 0x7149f2ca, v222
	v_mfma_f32_16x16x32_bf16 v[76:79], v[76:79], v[140:143], v[248:251]
	v_max3_f32 v98, v98, v86, v87
	v_fmamk_f32 v80, v223, 0x7149f2ca, v80
	v_fmamk_f32 v81, v224, 0x7149f2ca, v81
	v_max3_f32 v98, v98, v80, v81
	v_fmamk_f32 v82, v225, 0x7149f2ca, v82
	v_fmac_f32_e32 v83, 0x7149f2ca, v226
	v_max3_f32 v98, v98, v82, v83
	v_fmamk_f32 v116, v227, 0x7149f2ca, v72
	v_fmamk_f32 v118, v228, 0x7149f2ca, v73
	v_max3_f32 v72, v98, v116, v118
	v_fmamk_f32 v74, v229, 0x7149f2ca, v74
	v_fmac_f32_e32 v75, 0x7149f2ca, v230
	v_max3_f32 v72, v72, v74, v75
	v_fmamk_f32 v140, v231, 0x7149f2ca, v76
	v_fmamk_f32 v141, v232, 0x7149f2ca, v77
	v_max3_f32 v72, v72, v140, v141
	v_fmamk_f32 v78, v233, 0x7149f2ca, v78
	v_fmac_f32_e32 v79, 0x7149f2ca, v234
	v_max3_f32 v72, v72, v78, v79
	ds_bpermute_b32 v73, v109, v72
	s_waitcnt lgkmcnt(0)
	v_max_f32_e32 v73, v73, v73
	v_max_f32_e32 v72, v72, v73
	ds_bpermute_b32 v73, v139, v72
	s_waitcnt lgkmcnt(0)
; #define LAS __attribute__((address_space(3)))
; DI unsigned pk2(float lo, float hi) { return f2bf(lo) | (f2bf(hi) << 16); }
; DI void attn_tile(int j, int tile, LAS unsigned char* lds) {
;     ...
;             const float mn = fmaxf(mr[g], mx); const float alpha = __expf(mr[g] - mn);
;             float rs = 0.f;
; #pragma unroll
;             for (int nt = 0; nt < 8; ++nt) { float o[4];
; #pragma unroll
;                 for (int e = 0; e < 4; ++e) { o[e] = __expf(s[nt][e] - mn); rs += o[e]; }
;                 u32x2 w2; w2.x = pk2(o[0], o[1]); w2.y = pk2(o[2], o[3]);
;                 *(LAS u32x2*)(Ps + qi * 136 + nt * 16 + fq * 4) = w2; }
	v_max3_f32 v111, v69, v72, v73
	v_sub_f32_e32 v68, v68, v111
	v_sub_f32_e32 v72, v100, v111
	v_mul_f32_e32 v68, 0x3fb8aa3b, v68
	v_mul_f32_e32 v72, 0x3fb8aa3b, v72
	v_exp_f32_e32 v172, v68
	v_sub_f32_e32 v68, v96, v111
	v_exp_f32_e32 v150, v72
	v_sub_f32_e32 v72, v195, v111
	v_mul_f32_e32 v68, 0x3fb8aa3b, v68
	v_mul_f32_e32 v72, 0x3fb8aa3b, v72
	v_exp_f32_e32 v170, v68
	v_exp_f32_e32 v152, v72
	v_and_b32_sdwa v73, v172, v186 dst_sel:DWORD dst_unused:UNUSED_PAD src0_sel:WORD_1 src1_sel:DWORD
	v_add3_u32 v76, v172, v73, s31
	v_and_b32_sdwa v77, v170, v186 dst_sel:DWORD dst_unused:UNUSED_PAD src0_sel:WORD_1 src1_sel:DWORD
	v_and_b32_sdwa v73, v152, v186 dst_sel:DWORD dst_unused:UNUSED_PAD src0_sel:WORD_1 src1_sel:DWORD
	v_and_b32_sdwa v72, v150, v186 dst_sel:DWORD dst_unused:UNUSED_PAD src0_sel:WORD_1 src1_sel:DWORD
	v_add3_u32 v73, v152, v73, s31
	v_add3_u32 v77, v170, v77, s31
	v_add3_u32 v72, v150, v72, s31
	v_and_b32_e32 v73, 0xffff0000, v73
	v_and_b32_e32 v77, 0xffff0000, v77
	v_or_b32_sdwa v73, v73, v72 dst_sel:DWORD dst_unused:UNUSED_PAD src0_sel:DWORD src1_sel:WORD_1
	v_or_b32_sdwa v72, v77, v76 dst_sel:DWORD dst_unused:UNUSED_PAD src0_sel:DWORD src1_sel:WORD_1
	v_sub_f32_e32 v76, v102, v111
	v_mul_f32_e32 v76, 0x3fb8aa3b, v76
	v_exp_f32_e32 v154, v76
	v_sub_f32_e32 v76, v112, v111
	v_mul_f32_e32 v76, 0x3fb8aa3b, v76
	v_exp_f32_e32 v156, v76
	v_sub_f32_e32 v76, v114, v111
	v_mul_f32_e32 v76, 0x3fb8aa3b, v76
	v_exp_f32_e32 v158, v76
	v_sub_f32_e32 v76, v191, v111
	v_mul_f32_e32 v76, 0x3fb8aa3b, v76
	v_exp_f32_e32 v160, v76
	v_and_b32_sdwa v77, v154, v186 dst_sel:DWORD dst_unused:UNUSED_PAD src0_sel:WORD_1 src1_sel:DWORD
	v_add3_u32 v96, v154, v77, s31
	v_and_b32_sdwa v98, v156, v186 dst_sel:DWORD dst_unused:UNUSED_PAD src0_sel:WORD_1 src1_sel:DWORD
	v_and_b32_sdwa v77, v160, v186 dst_sel:DWORD dst_unused:UNUSED_PAD src0_sel:WORD_1 src1_sel:DWORD
	v_and_b32_sdwa v76, v158, v186 dst_sel:DWORD dst_unused:UNUSED_PAD src0_sel:WORD_1 src1_sel:DWORD
	v_add3_u32 v77, v160, v77, s31
	v_add3_u32 v98, v156, v98, s31
	v_add3_u32 v76, v158, v76, s31
	v_and_b32_e32 v77, 0xffff0000, v77
	v_and_b32_e32 v98, 0xffff0000, v98
	v_or_b32_sdwa v77, v77, v76 dst_sel:DWORD dst_unused:UNUSED_PAD src0_sel:DWORD src1_sel:WORD_1
	v_or_b32_sdwa v76, v98, v96 dst_sel:DWORD dst_unused:UNUSED_PAD src0_sel:DWORD src1_sel:WORD_1
	ds_write2_b64 v205, v[72:73], v[76:77] offset1:4
	v_sub_f32_e32 v72, v92, v111
	v_mul_f32_e32 v72, 0x3fb8aa3b, v72
	v_exp_f32_e32 v162, v72
	v_sub_f32_e32 v72, v93, v111
	v_mul_f32_e32 v72, 0x3fb8aa3b, v72
	v_exp_f32_e32 v164, v72
	v_sub_f32_e32 v72, v94, v111
	v_mul_f32_e32 v72, 0x3fb8aa3b, v72
	v_exp_f32_e32 v166, v72
	v_sub_f32_e32 v72, v95, v111
	v_mul_f32_e32 v72, 0x3fb8aa3b, v72
	v_exp_f32_e32 v168, v72
	v_and_b32_sdwa v73, v162, v186 dst_sel:DWORD dst_unused:UNUSED_PAD src0_sel:WORD_1 src1_sel:DWORD
	v_add3_u32 v76, v162, v73, s31
	v_and_b32_sdwa v77, v164, v186 dst_sel:DWORD dst_unused:UNUSED_PAD src0_sel:WORD_1 src1_sel:DWORD
	v_and_b32_sdwa v73, v168, v186 dst_sel:DWORD dst_unused:UNUSED_PAD src0_sel:WORD_1 src1_sel:DWORD
	v_and_b32_sdwa v72, v166, v186 dst_sel:DWORD dst_unused:UNUSED_PAD src0_sel:WORD_1 src1_sel:DWORD
	v_add3_u32 v73, v168, v73, s31
	v_add3_u32 v77, v164, v77, s31
	v_add3_u32 v72, v166, v72, s31
	v_and_b32_e32 v73, 0xffff0000, v73
	v_and_b32_e32 v77, 0xffff0000, v77
	v_or_b32_sdwa v73, v73, v72 dst_sel:DWORD dst_unused:UNUSED_PAD src0_sel:DWORD src1_sel:WORD_1
	v_or_b32_sdwa v72, v77, v76 dst_sel:DWORD dst_unused:UNUSED_PAD src0_sel:DWORD src1_sel:WORD_1
	v_sub_f32_e32 v76, v88, v111
	v_mul_f32_e32 v76, 0x3fb8aa3b, v76
	v_exp_f32_e32 v148, v76
	v_sub_f32_e32 v76, v89, v111
	v_mul_f32_e32 v76, 0x3fb8aa3b, v76
	v_exp_f32_e32 v128, v76
	v_sub_f32_e32 v76, v90, v111
	v_mul_f32_e32 v76, 0x3fb8aa3b, v76
	v_exp_f32_e32 v130, v76
	v_sub_f32_e32 v76, v91, v111
	v_mul_f32_e32 v76, 0x3fb8aa3b, v76
	v_exp_f32_e32 v132, v76
	v_and_b32_sdwa v77, v148, v186 dst_sel:DWORD dst_unused:UNUSED_PAD src0_sel:WORD_1 src1_sel:DWORD
	v_add3_u32 v88, v148, v77, s31
	v_and_b32_sdwa v89, v128, v186 dst_sel:DWORD dst_unused:UNUSED_PAD src0_sel:WORD_1 src1_sel:DWORD
	v_and_b32_sdwa v77, v132, v186 dst_sel:DWORD dst_unused:UNUSED_PAD src0_sel:WORD_1 src1_sel:DWORD
	v_and_b32_sdwa v76, v130, v186 dst_sel:DWORD dst_unused:UNUSED_PAD src0_sel:WORD_1 src1_sel:DWORD
	v_add3_u32 v77, v132, v77, s31
	v_add3_u32 v89, v128, v89, s31
	v_add3_u32 v76, v130, v76, s31
	v_and_b32_e32 v77, 0xffff0000, v77
	v_and_b32_e32 v89, 0xffff0000, v89
	v_or_b32_sdwa v77, v77, v76 dst_sel:DWORD dst_unused:UNUSED_PAD src0_sel:DWORD src1_sel:WORD_1
	v_or_b32_sdwa v76, v89, v88 dst_sel:DWORD dst_unused:UNUSED_PAD src0_sel:DWORD src1_sel:WORD_1
	ds_write2_b64 v205, v[72:73], v[76:77] offset0:8 offset1:12
	v_sub_f32_e32 v72, v84, v111
	v_mul_f32_e32 v72, 0x3fb8aa3b, v72
	v_exp_f32_e32 v134, v72
	v_sub_f32_e32 v72, v85, v111
	v_mul_f32_e32 v72, 0x3fb8aa3b, v72
	v_exp_f32_e32 v136, v72
	v_sub_f32_e32 v72, v86, v111
	v_mul_f32_e32 v72, 0x3fb8aa3b, v72
	v_exp_f32_e32 v144, v72
	v_sub_f32_e32 v72, v87, v111
	v_mul_f32_e32 v72, 0x3fb8aa3b, v72
	v_exp_f32_e32 v146, v72
	v_and_b32_sdwa v73, v134, v186 dst_sel:DWORD dst_unused:UNUSED_PAD src0_sel:WORD_1 src1_sel:DWORD
	v_add3_u32 v76, v134, v73, s31
	v_and_b32_sdwa v77, v136, v186 dst_sel:DWORD dst_unused:UNUSED_PAD src0_sel:WORD_1 src1_sel:DWORD
	v_and_b32_sdwa v73, v146, v186 dst_sel:DWORD dst_unused:UNUSED_PAD src0_sel:WORD_1 src1_sel:DWORD
	v_and_b32_sdwa v72, v144, v186 dst_sel:DWORD dst_unused:UNUSED_PAD src0_sel:WORD_1 src1_sel:DWORD
	v_add3_u32 v73, v146, v73, s31
	v_add3_u32 v77, v136, v77, s31
	v_add3_u32 v72, v144, v72, s31
; #define LAS __attribute__((address_space(3)))
; DI unsigned pk2(float lo, float hi) { return f2bf(lo) | (f2bf(hi) << 16); }
; DI void attn_tile(int j, int tile, LAS unsigned char* lds) {
;     ...
;             float rs = 0.f;
; #pragma unroll
;             for (int nt = 0; nt < 8; ++nt) { float o[4];
; #pragma unroll
;                 for (int e = 0; e < 4; ++e) { o[e] = __expf(s[nt][e] - mn); rs += o[e]; }
;                 u32x2 w2; w2.x = pk2(o[0], o[1]); w2.y = pk2(o[2], o[3]);
;                 *(LAS u32x2*)(Ps + qi * 136 + nt * 16 + fq * 4) = w2; }
;             rs += __shfl_xor(rs, 16); rs += __shfl_xor(rs, 32);
;             lr[g] = lr[g] * alpha + rs; mr[g] = mn;
	v_and_b32_e32 v73, 0xffff0000, v73
	v_and_b32_e32 v77, 0xffff0000, v77
	v_or_b32_sdwa v73, v73, v72 dst_sel:DWORD dst_unused:UNUSED_PAD src0_sel:DWORD src1_sel:WORD_1
	v_or_b32_sdwa v72, v77, v76 dst_sel:DWORD dst_unused:UNUSED_PAD src0_sel:DWORD src1_sel:WORD_1
	v_sub_f32_e32 v76, v80, v111
	v_mul_f32_e32 v76, 0x3fb8aa3b, v76
	v_exp_f32_e32 v122, v76
	v_sub_f32_e32 v76, v81, v111
	v_mul_f32_e32 v76, 0x3fb8aa3b, v76
	v_exp_f32_e32 v120, v76
	v_sub_f32_e32 v76, v82, v111
	v_mul_f32_e32 v76, 0x3fb8aa3b, v76
	v_exp_f32_e32 v126, v76
	v_sub_f32_e32 v76, v83, v111
	v_mul_f32_e32 v76, 0x3fb8aa3b, v76
	v_exp_f32_e32 v124, v76
	v_and_b32_sdwa v77, v122, v186 dst_sel:DWORD dst_unused:UNUSED_PAD src0_sel:WORD_1 src1_sel:DWORD
	v_add3_u32 v80, v122, v77, s31
	v_and_b32_sdwa v81, v120, v186 dst_sel:DWORD dst_unused:UNUSED_PAD src0_sel:WORD_1 src1_sel:DWORD
	v_and_b32_sdwa v77, v124, v186 dst_sel:DWORD dst_unused:UNUSED_PAD src0_sel:WORD_1 src1_sel:DWORD
	v_and_b32_sdwa v76, v126, v186 dst_sel:DWORD dst_unused:UNUSED_PAD src0_sel:WORD_1 src1_sel:DWORD
	v_add3_u32 v77, v124, v77, s31
	v_add3_u32 v81, v120, v81, s31
	v_sub_f32_e32 v69, v69, v111
	v_add3_u32 v76, v126, v76, s31
	v_and_b32_e32 v77, 0xffff0000, v77
	v_and_b32_e32 v81, 0xffff0000, v81
	v_mul_f32_e32 v142, 0x3fb8aa3b, v69
	v_pk_add_f32 v[68:69], v[172:173], 0 op_sel_hi:[1,0]
	v_or_b32_sdwa v77, v77, v76 dst_sel:DWORD dst_unused:UNUSED_PAD src0_sel:DWORD src1_sel:WORD_1
	v_or_b32_sdwa v76, v81, v80 dst_sel:DWORD dst_unused:UNUSED_PAD src0_sel:DWORD src1_sel:WORD_1
	v_pk_add_f32 v[68:69], v[170:171], v[68:69]
	ds_write2_b64 v205, v[72:73], v[76:77] offset0:16 offset1:20
	v_sub_f32_e32 v72, v116, v111
	v_pk_add_f32 v[68:69], v[150:151], v[68:69]
	v_mul_f32_e32 v72, 0x3fb8aa3b, v72
	v_pk_add_f32 v[68:69], v[152:153], v[68:69]
	v_exp_f32_e32 v96, v72
	v_sub_f32_e32 v72, v118, v111
	v_pk_add_f32 v[68:69], v[154:155], v[68:69]
	v_mul_f32_e32 v72, 0x3fb8aa3b, v72
	v_pk_add_f32 v[68:69], v[156:157], v[68:69]
	v_exp_f32_e32 v98, v72
	v_sub_f32_e32 v72, v74, v111
	v_pk_add_f32 v[68:69], v[158:159], v[68:69]
	v_mul_f32_e32 v72, 0x3fb8aa3b, v72
	v_pk_add_f32 v[68:69], v[160:161], v[68:69]
	v_exp_f32_e32 v100, v72
	v_sub_f32_e32 v72, v75, v111
	v_pk_add_f32 v[68:69], v[162:163], v[68:69]
	v_mul_f32_e32 v72, 0x3fb8aa3b, v72
	v_pk_add_f32 v[68:69], v[164:165], v[68:69]
	v_exp_f32_e32 v102, v72
	v_pk_add_f32 v[68:69], v[166:167], v[68:69]
	v_and_b32_sdwa v73, v96, v186 dst_sel:DWORD dst_unused:UNUSED_PAD src0_sel:WORD_1 src1_sel:DWORD
	v_pk_add_f32 v[68:69], v[168:169], v[68:69]
	v_add3_u32 v74, v96, v73, s31
	v_pk_add_f32 v[68:69], v[148:149], v[68:69]
	v_and_b32_sdwa v73, v102, v186 dst_sel:DWORD dst_unused:UNUSED_PAD src0_sel:WORD_1 src1_sel:DWORD
	v_pk_add_f32 v[68:69], v[128:129], v[68:69]
	v_and_b32_sdwa v75, v98, v186 dst_sel:DWORD dst_unused:UNUSED_PAD src0_sel:WORD_1 src1_sel:DWORD
	v_pk_add_f32 v[68:69], v[130:131], v[68:69]
	v_and_b32_sdwa v72, v100, v186 dst_sel:DWORD dst_unused:UNUSED_PAD src0_sel:WORD_1 src1_sel:DWORD
	v_add3_u32 v73, v102, v73, s31
	v_add3_u32 v75, v98, v75, s31
	v_pk_add_f32 v[68:69], v[132:133], v[68:69]
	v_add3_u32 v72, v100, v72, s31
	v_and_b32_e32 v73, 0xffff0000, v73
	v_and_b32_e32 v75, 0xffff0000, v75
	v_pk_add_f32 v[68:69], v[134:135], v[68:69]
	v_or_b32_sdwa v73, v73, v72 dst_sel:DWORD dst_unused:UNUSED_PAD src0_sel:DWORD src1_sel:WORD_1
	v_or_b32_sdwa v72, v75, v74 dst_sel:DWORD dst_unused:UNUSED_PAD src0_sel:DWORD src1_sel:WORD_1
	v_sub_f32_e32 v74, v140, v111
	v_pk_add_f32 v[68:69], v[136:137], v[68:69]
	v_mul_f32_e32 v74, 0x3fb8aa3b, v74
	v_pk_add_f32 v[68:69], v[144:145], v[68:69]
	v_exp_f32_e32 v112, v74
	v_sub_f32_e32 v74, v141, v111
	v_pk_add_f32 v[68:69], v[146:147], v[68:69]
	v_mul_f32_e32 v74, 0x3fb8aa3b, v74
	v_pk_add_f32 v[68:69], v[122:123], v[68:69]
	v_exp_f32_e32 v114, v74
	v_sub_f32_e32 v74, v78, v111
	v_pk_add_f32 v[68:69], v[120:121], v[68:69]
	v_mul_f32_e32 v74, 0x3fb8aa3b, v74
	v_pk_add_f32 v[68:69], v[126:127], v[68:69]
	v_exp_f32_e32 v116, v74
	v_sub_f32_e32 v74, v79, v111
	v_pk_add_f32 v[68:69], v[124:125], v[68:69]
	v_mul_f32_e32 v74, 0x3fb8aa3b, v74
	v_exp_f32_e32 v118, v74
	v_pk_add_f32 v[68:69], v[96:97], v[68:69]
	v_and_b32_sdwa v75, v112, v186 dst_sel:DWORD dst_unused:UNUSED_PAD src0_sel:WORD_1 src1_sel:DWORD
	v_pk_add_f32 v[68:69], v[98:99], v[68:69]
	v_add3_u32 v76, v112, v75, s31
	v_pk_add_f32 v[68:69], v[100:101], v[68:69]
	v_and_b32_sdwa v75, v118, v186 dst_sel:DWORD dst_unused:UNUSED_PAD src0_sel:WORD_1 src1_sel:DWORD
	v_pk_add_f32 v[68:69], v[102:103], v[68:69]
	v_and_b32_sdwa v77, v114, v186 dst_sel:DWORD dst_unused:UNUSED_PAD src0_sel:WORD_1 src1_sel:DWORD
	v_pk_add_f32 v[68:69], v[112:113], v[68:69]
	v_and_b32_sdwa v74, v116, v186 dst_sel:DWORD dst_unused:UNUSED_PAD src0_sel:WORD_1 src1_sel:DWORD
	v_add3_u32 v75, v118, v75, s31
	v_add3_u32 v77, v114, v77, s31
	v_pk_add_f32 v[68:69], v[114:115], v[68:69]
	v_add3_u32 v74, v116, v74, s31
	v_and_b32_e32 v75, 0xffff0000, v75
	v_and_b32_e32 v77, 0xffff0000, v77
	v_pk_add_f32 v[68:69], v[116:117], v[68:69]
	v_or_b32_sdwa v75, v75, v74 dst_sel:DWORD dst_unused:UNUSED_PAD src0_sel:DWORD src1_sel:WORD_1
	v_or_b32_sdwa v74, v77, v76 dst_sel:DWORD dst_unused:UNUSED_PAD src0_sel:DWORD src1_sel:WORD_1
	v_pk_add_f32 v[68:69], v[118:119], v[68:69]
	ds_write2_b64 v205, v[72:73], v[74:75] offset0:24 offset1:28
	ds_bpermute_b32 v75, v109, v69
	ds_bpermute_b32 v74, v109, v68
	v_exp_f32_e32 v72, v142
	v_mov_b32_e32 v73, v0
	s_waitcnt lgkmcnt(0)
; DI void attn_tile(int j, int tile, LAS unsigned char* lds) {
;     ...
;             mm16<8, 2>(Qs + g * 128 * 72 + wave * 16 * 72, 72, Ks, 72, s, fr, fq);
;     ...
;             rs += __shfl_xor(rs, 16); rs += __shfl_xor(rs, 32);
;             lr[g] = lr[g] * alpha + rs; mr[g] = mn;
; #pragma unroll
;             for (int i = 0; i < 4; ++i) O[g][i] *= alpha;
;             mm16<4, 4>(Ps + wave * 16 * 136, 136, VTs, 136, O[g], fr, fq);
	v_pk_add_f32 v[68:69], v[68:69], v[74:75]
	ds_bpermute_b32 v75, v139, v69
	ds_bpermute_b32 v74, v139, v68
	v_pk_mul_f32 v[50:51], v[50:51], v[72:73] op_sel_hi:[1,0]
	v_pk_mul_f32 v[48:49], v[48:49], v[72:73] op_sel_hi:[1,0]
	v_pk_mul_f32 v[46:47], v[46:47], v[72:73] op_sel_hi:[1,0]
	v_pk_mul_f32 v[44:45], v[44:45], v[72:73] op_sel_hi:[1,0]
	s_waitcnt lgkmcnt(0)
	v_pk_add_f32 v[68:69], v[68:69], v[74:75]
	v_pk_mul_f32 v[42:43], v[42:43], v[72:73] op_sel_hi:[1,0]
	v_pk_fma_f32 v[104:105], v[104:105], v[72:73], v[68:69]
	v_pk_mul_f32 v[40:41], v[40:41], v[72:73] op_sel_hi:[1,0]
	v_pk_mul_f32 v[38:39], v[38:39], v[72:73] op_sel_hi:[1,0]
	v_pk_mul_f32 v[36:37], v[36:37], v[72:73] op_sel_hi:[1,0]
	ds_read_b128 v[72:75], v202
	ds_read_b128 v[76:79], v206
	s_waitcnt lgkmcnt(0)
	v_mfma_f32_16x16x32_bf16 v[48:51], v[76:79], v[72:75], v[48:51]
	ds_read_b128 v[76:79], v206 offset:4352
	s_waitcnt lgkmcnt(0)
	v_mfma_f32_16x16x32_bf16 v[44:47], v[76:79], v[72:75], v[44:47]
	ds_read_b128 v[76:79], v206 offset:8704
	s_waitcnt lgkmcnt(0)
	v_mfma_f32_16x16x32_bf16 v[40:43], v[76:79], v[72:75], v[40:43]
	ds_read_b128 v[76:79], v206 offset:13056
	s_waitcnt lgkmcnt(0)
	v_mfma_f32_16x16x32_bf16 v[36:39], v[76:79], v[72:75], v[36:39]
	ds_read_b128 v[72:75], v202 offset:64
	ds_read_b128 v[76:79], v206 offset:64
	s_waitcnt lgkmcnt(0)
	v_mfma_f32_16x16x32_bf16 v[48:51], v[76:79], v[72:75], v[48:51]
	ds_read_b128 v[76:79], v206 offset:4416
	s_waitcnt lgkmcnt(0)
	v_mfma_f32_16x16x32_bf16 v[44:47], v[76:79], v[72:75], v[44:47]
	ds_read_b128 v[76:79], v206 offset:8768
	s_waitcnt lgkmcnt(0)
	v_mfma_f32_16x16x32_bf16 v[40:43], v[76:79], v[72:75], v[40:43]
	ds_read_b128 v[76:79], v206 offset:13120
	s_waitcnt lgkmcnt(0)
	v_mfma_f32_16x16x32_bf16 v[36:39], v[76:79], v[72:75], v[36:39]
	ds_read_b128 v[72:75], v202 offset:128
	ds_read_b128 v[76:79], v206 offset:128
	s_waitcnt lgkmcnt(0)
	v_mfma_f32_16x16x32_bf16 v[48:51], v[76:79], v[72:75], v[48:51]
	ds_read_b128 v[76:79], v206 offset:4480
	s_waitcnt lgkmcnt(0)
	v_mfma_f32_16x16x32_bf16 v[44:47], v[76:79], v[72:75], v[44:47]
	ds_read_b128 v[76:79], v206 offset:8832
	s_waitcnt lgkmcnt(0)
	v_mfma_f32_16x16x32_bf16 v[40:43], v[76:79], v[72:75], v[40:43]
	ds_read_b128 v[76:79], v206 offset:13184
	s_waitcnt lgkmcnt(0)
	v_mfma_f32_16x16x32_bf16 v[36:39], v[76:79], v[72:75], v[36:39]
	ds_read_b128 v[72:75], v202 offset:192
	ds_read_b128 v[76:79], v206 offset:192
	s_waitcnt lgkmcnt(0)
	v_mfma_f32_16x16x32_bf16 v[48:51], v[76:79], v[72:75], v[48:51]
	ds_read_b128 v[76:79], v206 offset:4544
	s_waitcnt lgkmcnt(0)
	v_mfma_f32_16x16x32_bf16 v[44:47], v[76:79], v[72:75], v[44:47]
	ds_read_b128 v[76:79], v206 offset:8896
	s_waitcnt lgkmcnt(0)
	v_mfma_f32_16x16x32_bf16 v[40:43], v[76:79], v[72:75], v[40:43]
	ds_read_b128 v[76:79], v206 offset:13248
	s_waitcnt lgkmcnt(0)
	v_mfma_f32_16x16x32_bf16 v[36:39], v[76:79], v[72:75], v[36:39]
	ds_read_b128 v[72:75], v201 offset:36864
	ds_read_b128 v[76:79], v204
	ds_read_b128 v[88:91], v204 offset:6912
	ds_read_b128 v[92:95], v204 offset:9216
	s_waitcnt lgkmcnt(0)
	v_mfma_f32_16x16x32_bf16 v[100:103], v[92:95], v[72:75], 0
	ds_read_b128 v[92:95], v204 offset:11520
	ds_read_b128 v[80:83], v204 offset:2304
	ds_read_b128 v[84:87], v204 offset:4608
	s_waitcnt lgkmcnt(2)
	v_mfma_f32_16x16x32_bf16 v[112:115], v[92:95], v[72:75], 0
	ds_read_b128 v[92:95], v204 offset:13824
	s_waitcnt lgkmcnt(0)
	v_mfma_f32_16x16x32_bf16 v[116:119], v[92:95], v[72:75], 0
	ds_read_b128 v[92:95], v204 offset:16128
	v_mfma_f32_16x16x32_bf16 v[76:79], v[76:79], v[72:75], 0
	v_mfma_f32_16x16x32_bf16 v[80:83], v[80:83], v[72:75], 0
	v_mfma_f32_16x16x32_bf16 v[84:87], v[84:87], v[72:75], 0
	v_mfma_f32_16x16x32_bf16 v[88:91], v[88:91], v[72:75], 0
	s_waitcnt lgkmcnt(0)
	v_mfma_f32_16x16x32_bf16 v[72:75], v[92:95], v[72:75], 0
	ds_read_b128 v[120:123], v201 offset:36928
	ds_read_b128 v[92:95], v204 offset:64
	s_waitcnt lgkmcnt(0)
	v_mfma_f32_16x16x32_bf16 v[124:127], v[92:95], v[120:123], v[76:79]
	s_nop 2
	ds_read_b128 v[76:79], v204 offset:2368
	s_waitcnt lgkmcnt(0)
	v_mfma_f32_16x16x32_bf16 v[96:99], v[76:79], v[120:123], v[80:83]
	ds_read_b128 v[76:79], v204 offset:4672
	s_nop 0
	v_fmamk_f32 v69, v174, 0x7149f2ca, v124
	v_fmac_f32_e32 v127, 0x7149f2ca, v180
	s_waitcnt lgkmcnt(0)
	v_mfma_f32_16x16x32_bf16 v[92:95], v[76:79], v[120:123], v[84:87]
	ds_read_b128 v[76:79], v204 offset:6976
	s_nop 0
	v_fmamk_f32 v96, v207, 0x7149f2ca, v96
	v_fmamk_f32 v97, v208, 0x7149f2ca, v97
	s_waitcnt lgkmcnt(0)
	v_mfma_f32_16x16x32_bf16 v[88:91], v[76:79], v[120:123], v[88:91]
	ds_read_b128 v[76:79], v204 offset:9280
	v_fmamk_f32 v98, v209, 0x7149f2ca, v98
	v_fmac_f32_e32 v99, 0x7149f2ca, v210
	s_waitcnt lgkmcnt(0)
	v_mfma_f32_16x16x32_bf16 v[84:87], v[76:79], v[120:123], v[100:103]
	ds_read_b128 v[76:79], v204 offset:11584
	s_nop 1
	ds_read_b128 v[100:103], v204 offset:16192
	v_fmamk_f32 v94, v213, 0x7149f2ca, v94
	s_waitcnt lgkmcnt(1)
	v_mfma_f32_16x16x32_bf16 v[80:83], v[76:79], v[120:123], v[112:115]
	ds_read_b128 v[76:79], v204 offset:13888
	v_fmac_f32_e32 v95, 0x7149f2ca, v214
	s_nop 0
	v_fmamk_f32 v113, v215, 0x7149f2ca, v88
	s_waitcnt lgkmcnt(1)
	v_mfma_f32_16x16x32_bf16 v[72:75], v[100:103], v[120:123], v[72:75]
	v_fmamk_f32 v100, v176, 0x7149f2ca, v125
	v_max3_f32 v0, v69, s2, v100
	v_fmamk_f32 v101, v178, 0x7149f2ca, v126
	v_max3_f32 v0, v0, v101, v127
	v_max3_f32 v0, v0, v96, v97
	v_max3_f32 v0, v0, v98, v99
	v_fmamk_f32 v102, v211, 0x7149f2ca, v92
	v_fmamk_f32 v103, v212, 0x7149f2ca, v93
	v_max3_f32 v0, v0, v102, v103
	v_max3_f32 v0, v0, v94, v95
	v_fmamk_f32 v114, v216, 0x7149f2ca, v89
	v_max3_f32 v0, v0, v113, v114
	v_fmamk_f32 v90, v217, 0x7149f2ca, v90
	v_fmac_f32_e32 v91, 0x7149f2ca, v218
	s_waitcnt lgkmcnt(0)
; #define LAS __attribute__((address_space(3)))
; DI unsigned pk2(float lo, float hi) { return f2bf(lo) | (f2bf(hi) << 16); }
; DI void attn_tile(int j, int tile, LAS unsigned char* lds) {
;     ...
;                 for (int e = 0; e < 4; ++e) { const float tf = fmaf(sgnf, (float)(nt * 16 + e), basef);
;                     s[nt][e] += fminf(tf, 0.f) * 1.0e30f; mx = fmaxf(mx, s[nt][e]); }
;             mx = fmaxf(mx, __shfl_xor(mx, 16)); mx = fmaxf(mx, __shfl_xor(mx, 32));
;             const float mn = fmaxf(mr[g], mx); const float alpha = __expf(mr[g] - mn);
;             float rs = 0.f;
; #pragma unroll
;             for (int nt = 0; nt < 8; ++nt) { float o[4];
; #pragma unroll
;                 for (int e = 0; e < 4; ++e) { o[e] = __expf(s[nt][e] - mn); rs += o[e]; }
;                 u32x2 w2; w2.x = pk2(o[0], o[1]); w2.y = pk2(o[2], o[3]);
;                 *(LAS u32x2*)(Ps + qi * 136 + nt * 16 + fq * 4) = w2; }
	v_mfma_f32_16x16x32_bf16 v[76:79], v[76:79], v[120:123], v[116:119]
	v_max3_f32 v0, v0, v90, v91
	v_fmamk_f32 v89, v219, 0x7149f2ca, v84
	v_fmamk_f32 v88, v220, 0x7149f2ca, v85
	v_max3_f32 v0, v0, v89, v88
	v_fmamk_f32 v86, v221, 0x7149f2ca, v86
	v_fmac_f32_e32 v87, 0x7149f2ca, v222
	v_max3_f32 v0, v0, v86, v87
	v_fmamk_f32 v85, v223, 0x7149f2ca, v80
	v_fmamk_f32 v84, v224, 0x7149f2ca, v81
	v_max3_f32 v0, v0, v85, v84
	v_fmamk_f32 v82, v225, 0x7149f2ca, v82
	v_fmac_f32_e32 v83, 0x7149f2ca, v226
	v_max3_f32 v0, v0, v82, v83
	v_fmamk_f32 v81, v227, 0x7149f2ca, v76
	v_fmamk_f32 v80, v228, 0x7149f2ca, v77
	v_max3_f32 v0, v0, v81, v80
	v_fmamk_f32 v78, v229, 0x7149f2ca, v78
	v_fmac_f32_e32 v79, 0x7149f2ca, v230
	v_max3_f32 v0, v0, v78, v79
	v_fmamk_f32 v77, v231, 0x7149f2ca, v72
	v_fmamk_f32 v76, v232, 0x7149f2ca, v73
	v_max3_f32 v0, v0, v77, v76
	v_fmamk_f32 v68, v233, 0x7149f2ca, v74
	v_fmac_f32_e32 v75, 0x7149f2ca, v234
	v_max3_f32 v0, v0, v68, v75
	ds_bpermute_b32 v72, v109, v0
	s_waitcnt lgkmcnt(0)
	v_max_f32_e32 v72, v72, v72
	v_max_f32_e32 v0, v0, v72
	ds_bpermute_b32 v72, v139, v0
	s_waitcnt lgkmcnt(0)
	v_max3_f32 v112, v70, v0, v72
	v_sub_f32_e32 v69, v69, v112
	v_mul_f32_e32 v69, 0x3fb8aa3b, v69
	v_exp_f32_e32 v125, v69
	v_sub_f32_e32 v69, v100, v112
	v_sub_f32_e32 v0, v70, v112
	v_mul_f32_e32 v69, 0x3fb8aa3b, v69
	v_sub_f32_e32 v70, v127, v112
	v_exp_f32_e32 v123, v69
	v_sub_f32_e32 v69, v101, v112
	v_mul_f32_e32 v70, 0x3fb8aa3b, v70
	v_mul_f32_e32 v69, 0x3fb8aa3b, v69
	v_exp_f32_e32 v115, v70
	v_exp_f32_e32 v69, v69
	v_and_b32_sdwa v74, v123, v186 dst_sel:DWORD dst_unused:UNUSED_PAD src0_sel:WORD_1 src1_sel:DWORD
	v_and_b32_sdwa v72, v125, v186 dst_sel:DWORD dst_unused:UNUSED_PAD src0_sel:WORD_1 src1_sel:DWORD
	v_and_b32_sdwa v73, v115, v186 dst_sel:DWORD dst_unused:UNUSED_PAD src0_sel:WORD_1 src1_sel:DWORD
	v_and_b32_sdwa v70, v69, v186 dst_sel:DWORD dst_unused:UNUSED_PAD src0_sel:WORD_1 src1_sel:DWORD
	v_add3_u32 v73, v115, v73, s31
	v_add3_u32 v70, v69, v70, s31
	v_and_b32_e32 v73, 0xffff0000, v73
	v_or_b32_sdwa v73, v73, v70 dst_sel:DWORD dst_unused:UNUSED_PAD src0_sel:DWORD src1_sel:WORD_1
	v_sub_f32_e32 v70, v96, v112
	v_mul_f32_e32 v70, 0x3fb8aa3b, v70
	v_exp_f32_e32 v121, v70
	v_sub_f32_e32 v70, v97, v112
	v_mul_f32_e32 v70, 0x3fb8aa3b, v70
	v_exp_f32_e32 v119, v70
	v_sub_f32_e32 v70, v98, v112
	v_mul_f32_e32 v70, 0x3fb8aa3b, v70
	v_exp_f32_e32 v117, v70
	v_sub_f32_e32 v70, v99, v112
	v_mul_f32_e32 v70, 0x3fb8aa3b, v70
	v_exp_f32_e32 v127, v70
	v_and_b32_sdwa v70, v117, v186 dst_sel:DWORD dst_unused:UNUSED_PAD src0_sel:WORD_1 src1_sel:DWORD
	v_and_b32_sdwa v93, v119, v186 dst_sel:DWORD dst_unused:UNUSED_PAD src0_sel:WORD_1 src1_sel:DWORD
	v_add3_u32 v70, v117, v70, s31
	v_and_b32_sdwa v92, v127, v186 dst_sel:DWORD dst_unused:UNUSED_PAD src0_sel:WORD_1 src1_sel:DWORD
	v_add3_u32 v92, v127, v92, s31
	v_add3_u32 v93, v119, v93, s31
	v_and_b32_e32 v92, 0xffff0000, v92
	v_and_b32_e32 v96, 0xffff0000, v93
	v_or_b32_sdwa v93, v92, v70 dst_sel:DWORD dst_unused:UNUSED_PAD src0_sel:DWORD src1_sel:WORD_1
	v_sub_f32_e32 v70, v102, v112
	v_mul_f32_e32 v70, 0x3fb8aa3b, v70
	v_exp_f32_e32 v137, v70
	v_sub_f32_e32 v70, v103, v112
	v_mul_f32_e32 v70, 0x3fb8aa3b, v70
	v_exp_f32_e32 v135, v70
	v_sub_f32_e32 v70, v94, v112
	v_mul_f32_e32 v70, 0x3fb8aa3b, v70
	v_exp_f32_e32 v133, v70
	v_sub_f32_e32 v70, v95, v112
	v_add3_u32 v74, v123, v74, s31
	v_mul_f32_e32 v70, 0x3fb8aa3b, v70
	v_add3_u32 v72, v125, v72, s31
	v_and_b32_e32 v74, 0xffff0000, v74
	v_exp_f32_e32 v147, v70
	v_or_b32_sdwa v72, v74, v72 dst_sel:DWORD dst_unused:UNUSED_PAD src0_sel:DWORD src1_sel:WORD_1
	v_and_b32_sdwa v74, v121, v186 dst_sel:DWORD dst_unused:UNUSED_PAD src0_sel:WORD_1 src1_sel:DWORD
	v_add3_u32 v74, v121, v74, s31
	v_or_b32_sdwa v92, v96, v74 dst_sel:DWORD dst_unused:UNUSED_PAD src0_sel:DWORD src1_sel:WORD_1
	ds_write2_b64 v205, v[72:73], v[92:93] offset1:4
	v_and_b32_sdwa v73, v147, v186 dst_sel:DWORD dst_unused:UNUSED_PAD src0_sel:WORD_1 src1_sel:DWORD
	v_and_b32_sdwa v70, v133, v186 dst_sel:DWORD dst_unused:UNUSED_PAD src0_sel:WORD_1 src1_sel:DWORD
	v_add3_u32 v73, v147, v73, s31
	v_add3_u32 v70, v133, v70, s31
	v_and_b32_e32 v73, 0xffff0000, v73
	v_or_b32_sdwa v73, v73, v70 dst_sel:DWORD dst_unused:UNUSED_PAD src0_sel:DWORD src1_sel:WORD_1
	v_sub_f32_e32 v70, v113, v112
	v_mul_f32_e32 v70, 0x3fb8aa3b, v70
	v_exp_f32_e32 v145, v70
	v_sub_f32_e32 v70, v114, v112
	v_mul_f32_e32 v70, 0x3fb8aa3b, v70
	v_exp_f32_e32 v131, v70
	v_sub_f32_e32 v70, v90, v112
	v_mul_f32_e32 v70, 0x3fb8aa3b, v70
	v_exp_f32_e32 v129, v70
	v_sub_f32_e32 v70, v91, v112
	v_mul_f32_e32 v70, 0x3fb8aa3b, v70
	v_exp_f32_e32 v149, v70
	v_and_b32_sdwa v70, v129, v186 dst_sel:DWORD dst_unused:UNUSED_PAD src0_sel:WORD_1 src1_sel:DWORD
	v_and_b32_sdwa v91, v131, v186 dst_sel:DWORD dst_unused:UNUSED_PAD src0_sel:WORD_1 src1_sel:DWORD
	v_add3_u32 v70, v129, v70, s31
	v_and_b32_sdwa v90, v149, v186 dst_sel:DWORD dst_unused:UNUSED_PAD src0_sel:WORD_1 src1_sel:DWORD
	v_add3_u32 v90, v149, v90, s31
	v_add3_u32 v91, v131, v91, s31
	v_and_b32_e32 v90, 0xffff0000, v90
	v_and_b32_e32 v92, 0xffff0000, v91
	v_or_b32_sdwa v91, v90, v70 dst_sel:DWORD dst_unused:UNUSED_PAD src0_sel:DWORD src1_sel:WORD_1
	v_sub_f32_e32 v70, v89, v112
	v_mul_f32_e32 v70, 0x3fb8aa3b, v70
	v_exp_f32_e32 v155, v70
	v_sub_f32_e32 v70, v88, v112
	v_mul_f32_e32 v70, 0x3fb8aa3b, v70
	v_exp_f32_e32 v153, v70
	v_sub_f32_e32 v70, v86, v112
	v_mul_f32_e32 v70, 0x3fb8aa3b, v70
	v_and_b32_sdwa v74, v135, v186 dst_sel:DWORD dst_unused:UNUSED_PAD src0_sel:WORD_1 src1_sel:DWORD
	v_exp_f32_e32 v151, v70
	v_sub_f32_e32 v70, v87, v112
; #define LAS __attribute__((address_space(3)))
; DI unsigned pk2(float lo, float hi) { return f2bf(lo) | (f2bf(hi) << 16); }
; DI void attn_tile(int j, int tile, LAS unsigned char* lds) {
;     ...
;             for (int nt = 0; nt < 8; ++nt) { float o[4];
; #pragma unroll
;                 for (int e = 0; e < 4; ++e) { o[e] = __expf(s[nt][e] - mn); rs += o[e]; }
;                 u32x2 w2; w2.x = pk2(o[0], o[1]); w2.y = pk2(o[2], o[3]);
;                 *(LAS u32x2*)(Ps + qi * 136 + nt * 16 + fq * 4) = w2; }
;             rs += __shfl_xor(rs, 16); rs += __shfl_xor(rs, 32);
;             lr[g] = lr[g] * alpha + rs; mr[g] = mn;
; #pragma unroll
;             for (int i = 0; i < 4; ++i) O[g][i] *= alpha;
;             mm16<4, 4>(Ps + wave * 16 * 136, 136, VTs, 136, O[g], fr, fq);
	v_and_b32_sdwa v72, v137, v186 dst_sel:DWORD dst_unused:UNUSED_PAD src0_sel:WORD_1 src1_sel:DWORD
	v_add3_u32 v74, v135, v74, s31
	v_mul_f32_e32 v70, 0x3fb8aa3b, v70
	v_add3_u32 v72, v137, v72, s31
	v_and_b32_e32 v74, 0xffff0000, v74
	v_exp_f32_e32 v163, v70
	v_or_b32_sdwa v72, v74, v72 dst_sel:DWORD dst_unused:UNUSED_PAD src0_sel:DWORD src1_sel:WORD_1
	v_and_b32_sdwa v74, v145, v186 dst_sel:DWORD dst_unused:UNUSED_PAD src0_sel:WORD_1 src1_sel:DWORD
	v_add3_u32 v74, v145, v74, s31
	v_or_b32_sdwa v90, v92, v74 dst_sel:DWORD dst_unused:UNUSED_PAD src0_sel:DWORD src1_sel:WORD_1
	ds_write2_b64 v205, v[72:73], v[90:91] offset0:8 offset1:12
	v_and_b32_sdwa v73, v163, v186 dst_sel:DWORD dst_unused:UNUSED_PAD src0_sel:WORD_1 src1_sel:DWORD
	v_and_b32_sdwa v70, v151, v186 dst_sel:DWORD dst_unused:UNUSED_PAD src0_sel:WORD_1 src1_sel:DWORD
	v_add3_u32 v73, v163, v73, s31
	v_add3_u32 v70, v151, v70, s31
	v_and_b32_e32 v73, 0xffff0000, v73
	v_or_b32_sdwa v73, v73, v70 dst_sel:DWORD dst_unused:UNUSED_PAD src0_sel:DWORD src1_sel:WORD_1
	v_sub_f32_e32 v70, v85, v112
	v_mul_f32_e32 v70, 0x3fb8aa3b, v70
	v_exp_f32_e32 v159, v70
	v_sub_f32_e32 v70, v84, v112
	v_mul_f32_e32 v70, 0x3fb8aa3b, v70
	v_exp_f32_e32 v157, v70
	v_sub_f32_e32 v70, v82, v112
	v_mul_f32_e32 v70, 0x3fb8aa3b, v70
	v_exp_f32_e32 v161, v70
	v_sub_f32_e32 v70, v83, v112
	v_mul_f32_e32 v70, 0x3fb8aa3b, v70
	v_exp_f32_e32 v171, v70
	v_and_b32_sdwa v70, v161, v186 dst_sel:DWORD dst_unused:UNUSED_PAD src0_sel:WORD_1 src1_sel:DWORD
	v_and_b32_sdwa v83, v157, v186 dst_sel:DWORD dst_unused:UNUSED_PAD src0_sel:WORD_1 src1_sel:DWORD
	v_add3_u32 v70, v161, v70, s31
	v_and_b32_sdwa v82, v171, v186 dst_sel:DWORD dst_unused:UNUSED_PAD src0_sel:WORD_1 src1_sel:DWORD
	v_add3_u32 v82, v171, v82, s31
	v_add3_u32 v83, v157, v83, s31
	v_and_b32_e32 v82, 0xffff0000, v82
	v_and_b32_e32 v84, 0xffff0000, v83
	v_or_b32_sdwa v83, v82, v70 dst_sel:DWORD dst_unused:UNUSED_PAD src0_sel:DWORD src1_sel:WORD_1
	v_sub_f32_e32 v70, v81, v112
	v_mul_f32_e32 v70, 0x3fb8aa3b, v70
	v_exp_f32_e32 v165, v70
	v_sub_f32_e32 v70, v80, v112
	v_mul_f32_e32 v70, 0x3fb8aa3b, v70
	v_exp_f32_e32 v167, v70
	v_sub_f32_e32 v70, v78, v112
	v_mul_f32_e32 v70, 0x3fb8aa3b, v70
	v_and_b32_sdwa v74, v153, v186 dst_sel:DWORD dst_unused:UNUSED_PAD src0_sel:WORD_1 src1_sel:DWORD
	v_exp_f32_e32 v169, v70
	v_sub_f32_e32 v70, v79, v112
	v_and_b32_sdwa v72, v155, v186 dst_sel:DWORD dst_unused:UNUSED_PAD src0_sel:WORD_1 src1_sel:DWORD
	v_add3_u32 v74, v153, v74, s31
	v_mul_f32_e32 v70, 0x3fb8aa3b, v70
	v_add3_u32 v72, v155, v72, s31
	v_and_b32_e32 v74, 0xffff0000, v74
	v_exp_f32_e32 v173, v70
	v_or_b32_sdwa v72, v74, v72 dst_sel:DWORD dst_unused:UNUSED_PAD src0_sel:DWORD src1_sel:WORD_1
	v_and_b32_sdwa v74, v159, v186 dst_sel:DWORD dst_unused:UNUSED_PAD src0_sel:WORD_1 src1_sel:DWORD
	v_add3_u32 v74, v159, v74, s31
	v_or_b32_sdwa v82, v84, v74 dst_sel:DWORD dst_unused:UNUSED_PAD src0_sel:DWORD src1_sel:WORD_1
	ds_write2_b64 v205, v[72:73], v[82:83] offset0:16 offset1:20
	v_and_b32_sdwa v73, v173, v186 dst_sel:DWORD dst_unused:UNUSED_PAD src0_sel:WORD_1 src1_sel:DWORD
	v_and_b32_sdwa v70, v169, v186 dst_sel:DWORD dst_unused:UNUSED_PAD src0_sel:WORD_1 src1_sel:DWORD
	v_add3_u32 v73, v173, v73, s31
	v_add3_u32 v70, v169, v70, s31
	v_and_b32_e32 v73, 0xffff0000, v73
	v_or_b32_sdwa v73, v73, v70 dst_sel:DWORD dst_unused:UNUSED_PAD src0_sel:DWORD src1_sel:WORD_1
	v_sub_f32_e32 v70, v77, v112
	v_sub_f32_e32 v68, v68, v112
	v_mul_f32_e32 v70, 0x3fb8aa3b, v70
	v_mul_f32_e32 v68, 0x3fb8aa3b, v68
	v_exp_f32_e32 v175, v70
	v_sub_f32_e32 v70, v76, v112
	v_exp_f32_e32 v179, v68
	v_sub_f32_e32 v68, v75, v112
	v_mul_f32_e32 v70, 0x3fb8aa3b, v70
	v_mul_f32_e32 v68, 0x3fb8aa3b, v68
	v_exp_f32_e32 v177, v70
	v_exp_f32_e32 v181, v68
	v_and_b32_sdwa v74, v167, v186 dst_sel:DWORD dst_unused:UNUSED_PAD src0_sel:WORD_1 src1_sel:DWORD
	v_and_b32_sdwa v72, v165, v186 dst_sel:DWORD dst_unused:UNUSED_PAD src0_sel:WORD_1 src1_sel:DWORD
	v_add3_u32 v74, v167, v74, s31
	v_add3_u32 v72, v165, v72, s31
	v_and_b32_e32 v74, 0xffff0000, v74
	v_or_b32_sdwa v72, v74, v72 dst_sel:DWORD dst_unused:UNUSED_PAD src0_sel:DWORD src1_sel:WORD_1
	v_and_b32_sdwa v74, v181, v186 dst_sel:DWORD dst_unused:UNUSED_PAD src0_sel:WORD_1 src1_sel:DWORD
	v_and_b32_sdwa v75, v177, v186 dst_sel:DWORD dst_unused:UNUSED_PAD src0_sel:WORD_1 src1_sel:DWORD
	v_and_b32_sdwa v68, v179, v186 dst_sel:DWORD dst_unused:UNUSED_PAD src0_sel:WORD_1 src1_sel:DWORD
	v_and_b32_sdwa v70, v175, v186 dst_sel:DWORD dst_unused:UNUSED_PAD src0_sel:WORD_1 src1_sel:DWORD
	v_add3_u32 v74, v181, v74, s31
	v_add3_u32 v75, v177, v75, s31
	v_add3_u32 v70, v175, v70, s31
	v_add3_u32 v68, v179, v68, s31
	v_and_b32_e32 v74, 0xffff0000, v74
	v_and_b32_e32 v76, 0xffff0000, v75
	v_or_b32_sdwa v75, v74, v68 dst_sel:DWORD dst_unused:UNUSED_PAD src0_sel:DWORD src1_sel:WORD_1
	v_or_b32_sdwa v74, v76, v70 dst_sel:DWORD dst_unused:UNUSED_PAD src0_sel:DWORD src1_sel:WORD_1
	v_mul_f32_e32 v0, 0x3fb8aa3b, v0
	ds_write2_b64 v205, v[72:73], v[74:75] offset0:24 offset1:28
	v_exp_f32_e32 v0, v0
	ds_read_b128 v[72:75], v202
	ds_read_b128 v[76:79], v206
	v_pk_mul_f32 v[18:19], v[18:19], v[0:1] op_sel_hi:[1,0]
	v_pk_mul_f32 v[16:17], v[16:17], v[0:1] op_sel_hi:[1,0]
	v_pk_mul_f32 v[14:15], v[14:15], v[0:1] op_sel_hi:[1,0]
	v_pk_mul_f32 v[12:13], v[12:13], v[0:1] op_sel_hi:[1,0]
	s_waitcnt lgkmcnt(0)
	v_mfma_f32_16x16x32_bf16 v[16:19], v[76:79], v[72:75], v[16:19]
	ds_read_b128 v[76:79], v206 offset:4352
	v_pk_mul_f32 v[10:11], v[10:11], v[0:1] op_sel_hi:[1,0]
	v_pk_mul_f32 v[8:9], v[8:9], v[0:1] op_sel_hi:[1,0]
	s_waitcnt lgkmcnt(0)
; #define LAS __attribute__((address_space(3)))
; DI unsigned pk2(float lo, float hi) { return f2bf(lo) | (f2bf(hi) << 16); }
; DI void attn_tile(int j, int tile, LAS unsigned char* lds) {
;     ...
;             mm16<8, 2>(Qs + g * 128 * 72 + wave * 16 * 72, 72, Ks, 72, s, fr, fq);
;             const int qi = wave * 16 + fr;
;             float mx = -3.0e38f;
; #pragma unroll
;             for (int nt = 0; nt < 8; ++nt)
; #pragma unroll
;                 for (int e = 0; e < 4; ++e) { const float tf = fmaf(sgnf, (float)(nt * 16 + e), basef);
;                     s[nt][e] += fminf(tf, 0.f) * 1.0e30f; mx = fmaxf(mx, s[nt][e]); }
;             mx = fmaxf(mx, __shfl_xor(mx, 16)); mx = fmaxf(mx, __shfl_xor(mx, 32));
;             const float mn = fmaxf(mr[g], mx); const float alpha = __expf(mr[g] - mn);
;             float rs = 0.f;
; #pragma unroll
;             for (int nt = 0; nt < 8; ++nt) { float o[4];
; #pragma unroll
;                 for (int e = 0; e < 4; ++e) { o[e] = __expf(s[nt][e] - mn); rs += o[e]; }
;                 u32x2 w2; w2.x = pk2(o[0], o[1]); w2.y = pk2(o[2], o[3]);
;                 *(LAS u32x2*)(Ps + qi * 136 + nt * 16 + fq * 4) = w2; }
;             rs += __shfl_xor(rs, 16); rs += __shfl_xor(rs, 32);
;             lr[g] = lr[g] * alpha + rs; mr[g] = mn;
; #pragma unroll
;             for (int i = 0; i < 4; ++i) O[g][i] *= alpha;
;             mm16<4, 4>(Ps + wave * 16 * 136, 136, VTs, 136, O[g], fr, fq);
	v_mfma_f32_16x16x32_bf16 v[12:15], v[76:79], v[72:75], v[12:15]
	ds_read_b128 v[76:79], v206 offset:8704
	v_pk_mul_f32 v[6:7], v[6:7], v[0:1] op_sel_hi:[1,0]
	v_pk_mul_f32 v[4:5], v[4:5], v[0:1] op_sel_hi:[1,0]
	s_waitcnt lgkmcnt(0)
	v_mfma_f32_16x16x32_bf16 v[8:11], v[76:79], v[72:75], v[8:11]
	ds_read_b128 v[76:79], v206 offset:13056
	s_waitcnt lgkmcnt(0)
	v_mfma_f32_16x16x32_bf16 v[4:7], v[76:79], v[72:75], v[4:7]
	ds_read_b128 v[72:75], v202 offset:64
	ds_read_b128 v[76:79], v206 offset:64
	s_waitcnt lgkmcnt(0)
	v_mfma_f32_16x16x32_bf16 v[16:19], v[76:79], v[72:75], v[16:19]
	ds_read_b128 v[76:79], v206 offset:4416
	s_waitcnt lgkmcnt(0)
	v_mfma_f32_16x16x32_bf16 v[12:15], v[76:79], v[72:75], v[12:15]
	ds_read_b128 v[76:79], v206 offset:8768
	s_waitcnt lgkmcnt(0)
	v_mfma_f32_16x16x32_bf16 v[8:11], v[76:79], v[72:75], v[8:11]
	ds_read_b128 v[76:79], v206 offset:13120
	s_waitcnt lgkmcnt(0)
	v_mfma_f32_16x16x32_bf16 v[4:7], v[76:79], v[72:75], v[4:7]
	ds_read_b128 v[72:75], v202 offset:128
	ds_read_b128 v[76:79], v206 offset:128
	s_waitcnt lgkmcnt(0)
	v_mfma_f32_16x16x32_bf16 v[16:19], v[76:79], v[72:75], v[16:19]
	ds_read_b128 v[76:79], v206 offset:4480
	s_waitcnt lgkmcnt(0)
	v_mfma_f32_16x16x32_bf16 v[12:15], v[76:79], v[72:75], v[12:15]
	ds_read_b128 v[76:79], v206 offset:8832
	s_waitcnt lgkmcnt(0)
	v_mfma_f32_16x16x32_bf16 v[8:11], v[76:79], v[72:75], v[8:11]
	ds_read_b128 v[76:79], v206 offset:13184
	s_waitcnt lgkmcnt(0)
	v_mfma_f32_16x16x32_bf16 v[4:7], v[76:79], v[72:75], v[4:7]
	ds_read_b128 v[72:75], v202 offset:192
	ds_read_b128 v[76:79], v206 offset:192
	s_waitcnt lgkmcnt(0)
	v_mfma_f32_16x16x32_bf16 v[16:19], v[76:79], v[72:75], v[16:19]
	ds_read_b128 v[76:79], v206 offset:4544
	s_waitcnt lgkmcnt(0)
	v_mfma_f32_16x16x32_bf16 v[12:15], v[76:79], v[72:75], v[12:15]
	ds_read_b128 v[76:79], v206 offset:8896
	s_waitcnt lgkmcnt(0)
	v_mfma_f32_16x16x32_bf16 v[8:11], v[76:79], v[72:75], v[8:11]
	ds_read_b128 v[76:79], v206 offset:13248
	s_waitcnt lgkmcnt(0)
	v_mfma_f32_16x16x32_bf16 v[4:7], v[76:79], v[72:75], v[4:7]
	ds_read_b128 v[72:75], v201 offset:55296
	ds_read_b128 v[76:79], v204
	ds_read_b128 v[88:91], v204 offset:6912
	ds_read_b128 v[92:95], v204 offset:9216
	s_waitcnt lgkmcnt(0)
	v_mfma_f32_16x16x32_bf16 v[140:143], v[92:95], v[72:75], 0
	ds_read_b128 v[92:95], v204 offset:11520
	ds_read_b128 v[80:83], v204 offset:2304
	ds_read_b128 v[84:87], v204 offset:4608
	s_waitcnt lgkmcnt(2)
	v_mfma_f32_16x16x32_bf16 v[188:191], v[92:95], v[72:75], 0
	ds_read_b128 v[92:95], v204 offset:13824
	s_waitcnt lgkmcnt(0)
	v_mfma_f32_16x16x32_bf16 v[192:195], v[92:95], v[72:75], 0
	ds_read_b128 v[92:95], v204 offset:16128
	v_mfma_f32_16x16x32_bf16 v[76:79], v[76:79], v[72:75], 0
	v_mfma_f32_16x16x32_bf16 v[80:83], v[80:83], v[72:75], 0
	v_mfma_f32_16x16x32_bf16 v[84:87], v[84:87], v[72:75], 0
	v_mfma_f32_16x16x32_bf16 v[88:91], v[88:91], v[72:75], 0
	s_waitcnt lgkmcnt(0)
	v_mfma_f32_16x16x32_bf16 v[236:239], v[92:95], v[72:75], 0
	ds_read_b128 v[240:243], v201 offset:55360
	ds_read_b128 v[72:75], v204 offset:64
	s_waitcnt lgkmcnt(0)
	v_mfma_f32_16x16x32_bf16 v[100:103], v[72:75], v[240:243], v[76:79]
	ds_read_b128 v[72:75], v204 offset:2368
	s_nop 1
	ds_read_b128 v[76:79], v204 offset:16192
	s_waitcnt lgkmcnt(1)
	v_mfma_f32_16x16x32_bf16 v[96:99], v[72:75], v[240:243], v[80:83]
	ds_read_b128 v[72:75], v204 offset:4672
	s_nop 0
	v_fmamk_f32 v68, v174, 0x7149f2ca, v100
	v_fmamk_f32 v70, v176, 0x7149f2ca, v101
	s_waitcnt lgkmcnt(0)
	v_mfma_f32_16x16x32_bf16 v[92:95], v[72:75], v[240:243], v[84:87]
	ds_read_b128 v[72:75], v204 offset:6976
	v_max3_f32 v100, v68, s2, v70
	v_fmamk_f32 v101, v178, 0x7149f2ca, v102
	s_waitcnt lgkmcnt(0)
	v_mfma_f32_16x16x32_bf16 v[88:91], v[72:75], v[240:243], v[88:91]
	ds_read_b128 v[72:75], v204 offset:9280
	v_fmac_f32_e32 v103, 0x7149f2ca, v180
	v_max3_f32 v100, v100, v101, v103
	s_waitcnt lgkmcnt(0)
	v_mfma_f32_16x16x32_bf16 v[84:87], v[72:75], v[240:243], v[140:143]
	ds_read_b128 v[72:75], v204 offset:11584
	v_fmamk_f32 v96, v207, 0x7149f2ca, v96
	v_fmamk_f32 v97, v208, 0x7149f2ca, v97
	s_waitcnt lgkmcnt(0)
	v_mfma_f32_16x16x32_bf16 v[80:83], v[72:75], v[240:243], v[188:191]
	ds_read_b128 v[72:75], v204 offset:13888
	v_max3_f32 v100, v100, v96, v97
	v_fmamk_f32 v98, v209, 0x7149f2ca, v98
	v_fmac_f32_e32 v99, 0x7149f2ca, v210
	v_max3_f32 v100, v100, v98, v99
	v_fmamk_f32 v92, v211, 0x7149f2ca, v92
	v_fmamk_f32 v93, v212, 0x7149f2ca, v93
	v_max3_f32 v100, v100, v92, v93
	v_fmamk_f32 v94, v213, 0x7149f2ca, v94
	v_fmac_f32_e32 v95, 0x7149f2ca, v214
	v_max3_f32 v100, v100, v94, v95
	v_fmamk_f32 v88, v215, 0x7149f2ca, v88
	v_fmamk_f32 v89, v216, 0x7149f2ca, v89
	v_max3_f32 v100, v100, v88, v89
	v_fmamk_f32 v90, v217, 0x7149f2ca, v90
	v_fmac_f32_e32 v91, 0x7149f2ca, v218
	s_waitcnt lgkmcnt(0)
	v_mfma_f32_16x16x32_bf16 v[72:75], v[72:75], v[240:243], v[192:195]
	v_max3_f32 v100, v100, v90, v91
	v_fmamk_f32 v84, v219, 0x7149f2ca, v84
	v_fmamk_f32 v85, v220, 0x7149f2ca, v85
	v_max3_f32 v100, v100, v84, v85
	v_fmamk_f32 v86, v221, 0x7149f2ca, v86
	v_fmac_f32_e32 v87, 0x7149f2ca, v222
	v_mfma_f32_16x16x32_bf16 v[76:79], v[76:79], v[240:243], v[236:239]
	v_max3_f32 v100, v100, v86, v87
	v_fmamk_f32 v80, v223, 0x7149f2ca, v80
	v_fmamk_f32 v81, v224, 0x7149f2ca, v81
	v_max3_f32 v100, v100, v80, v81
	v_fmamk_f32 v82, v225, 0x7149f2ca, v82
	v_fmac_f32_e32 v83, 0x7149f2ca, v226
	v_max3_f32 v100, v100, v82, v83
	v_fmamk_f32 v102, v227, 0x7149f2ca, v72
	v_fmamk_f32 v140, v228, 0x7149f2ca, v73
	v_max3_f32 v72, v100, v102, v140
	v_fmamk_f32 v74, v229, 0x7149f2ca, v74
	v_fmac_f32_e32 v75, 0x7149f2ca, v230
	v_max3_f32 v72, v72, v74, v75
	v_fmamk_f32 v100, v231, 0x7149f2ca, v76
	v_fmamk_f32 v141, v232, 0x7149f2ca, v77
	v_max3_f32 v72, v72, v100, v141
	v_fmamk_f32 v78, v233, 0x7149f2ca, v78
	v_fmac_f32_e32 v79, 0x7149f2ca, v234
	v_max3_f32 v72, v72, v78, v79
	ds_bpermute_b32 v73, v109, v72
	s_waitcnt lgkmcnt(0)
; #define LAS __attribute__((address_space(3)))
; DI unsigned pk2(float lo, float hi) { return f2bf(lo) | (f2bf(hi) << 16); }
; DI void attn_tile(int j, int tile, LAS unsigned char* lds) {
;     ...
;             mx = fmaxf(mx, __shfl_xor(mx, 16)); mx = fmaxf(mx, __shfl_xor(mx, 32));
;             const float mn = fmaxf(mr[g], mx); const float alpha = __expf(mr[g] - mn);
;             float rs = 0.f;
; #pragma unroll
;             for (int nt = 0; nt < 8; ++nt) { float o[4];
; #pragma unroll
;                 for (int e = 0; e < 4; ++e) { o[e] = __expf(s[nt][e] - mn); rs += o[e]; }
;                 u32x2 w2; w2.x = pk2(o[0], o[1]); w2.y = pk2(o[2], o[3]);
;                 *(LAS u32x2*)(Ps + qi * 136 + nt * 16 + fq * 4) = w2; }
	v_max_f32_e32 v73, v73, v73
	v_max_f32_e32 v72, v72, v73
	ds_bpermute_b32 v73, v139, v72
	s_waitcnt lgkmcnt(0)
	v_max3_f32 v113, v71, v72, v73
	v_sub_f32_e32 v68, v68, v113
	v_mul_f32_e32 v68, 0x3fb8aa3b, v68
	v_exp_f32_e32 v124, v68
	v_sub_f32_e32 v68, v70, v113
	v_mul_f32_e32 v68, 0x3fb8aa3b, v68
	v_sub_f32_e32 v72, v103, v113
	v_exp_f32_e32 v122, v68
	v_sub_f32_e32 v68, v101, v113
	v_mul_f32_e32 v72, 0x3fb8aa3b, v72
	v_mul_f32_e32 v68, 0x3fb8aa3b, v68
	v_exp_f32_e32 v114, v72
	v_exp_f32_e32 v68, v68
	v_and_b32_sdwa v73, v124, v186 dst_sel:DWORD dst_unused:UNUSED_PAD src0_sel:WORD_1 src1_sel:DWORD
	v_add3_u32 v76, v124, v73, s31
	v_and_b32_sdwa v73, v114, v186 dst_sel:DWORD dst_unused:UNUSED_PAD src0_sel:WORD_1 src1_sel:DWORD
	v_and_b32_sdwa v77, v122, v186 dst_sel:DWORD dst_unused:UNUSED_PAD src0_sel:WORD_1 src1_sel:DWORD
	v_and_b32_sdwa v72, v68, v186 dst_sel:DWORD dst_unused:UNUSED_PAD src0_sel:WORD_1 src1_sel:DWORD
	v_add3_u32 v73, v114, v73, s31
	v_add3_u32 v77, v122, v77, s31
	v_add3_u32 v72, v68, v72, s31
	v_and_b32_e32 v73, 0xffff0000, v73
	v_and_b32_e32 v77, 0xffff0000, v77
	v_or_b32_sdwa v73, v73, v72 dst_sel:DWORD dst_unused:UNUSED_PAD src0_sel:DWORD src1_sel:WORD_1
	v_or_b32_sdwa v72, v77, v76 dst_sel:DWORD dst_unused:UNUSED_PAD src0_sel:DWORD src1_sel:WORD_1
	v_sub_f32_e32 v76, v96, v113
	v_mul_f32_e32 v76, 0x3fb8aa3b, v76
	v_exp_f32_e32 v120, v76
	v_sub_f32_e32 v76, v97, v113
	v_mul_f32_e32 v76, 0x3fb8aa3b, v76
	v_exp_f32_e32 v118, v76
	v_sub_f32_e32 v76, v98, v113
	v_mul_f32_e32 v76, 0x3fb8aa3b, v76
	v_exp_f32_e32 v116, v76
	v_sub_f32_e32 v76, v99, v113
	v_mul_f32_e32 v76, 0x3fb8aa3b, v76
	v_exp_f32_e32 v126, v76
	v_and_b32_sdwa v77, v120, v186 dst_sel:DWORD dst_unused:UNUSED_PAD src0_sel:WORD_1 src1_sel:DWORD
	v_add3_u32 v96, v120, v77, s31
	v_and_b32_sdwa v97, v118, v186 dst_sel:DWORD dst_unused:UNUSED_PAD src0_sel:WORD_1 src1_sel:DWORD
	v_and_b32_sdwa v77, v126, v186 dst_sel:DWORD dst_unused:UNUSED_PAD src0_sel:WORD_1 src1_sel:DWORD
	v_and_b32_sdwa v76, v116, v186 dst_sel:DWORD dst_unused:UNUSED_PAD src0_sel:WORD_1 src1_sel:DWORD
	v_add3_u32 v77, v126, v77, s31
	v_add3_u32 v97, v118, v97, s31
	v_add3_u32 v76, v116, v76, s31
	v_and_b32_e32 v77, 0xffff0000, v77
	v_and_b32_e32 v97, 0xffff0000, v97
	v_or_b32_sdwa v77, v77, v76 dst_sel:DWORD dst_unused:UNUSED_PAD src0_sel:DWORD src1_sel:WORD_1
	v_or_b32_sdwa v76, v97, v96 dst_sel:DWORD dst_unused:UNUSED_PAD src0_sel:DWORD src1_sel:WORD_1
	ds_write2_b64 v205, v[72:73], v[76:77] offset1:4
	v_sub_f32_e32 v72, v92, v113
	v_mul_f32_e32 v72, 0x3fb8aa3b, v72
	v_exp_f32_e32 v136, v72
	v_sub_f32_e32 v72, v93, v113
	v_mul_f32_e32 v72, 0x3fb8aa3b, v72
	v_exp_f32_e32 v134, v72
	v_sub_f32_e32 v72, v94, v113
	v_mul_f32_e32 v72, 0x3fb8aa3b, v72
	v_exp_f32_e32 v132, v72
	v_sub_f32_e32 v72, v95, v113
	v_mul_f32_e32 v72, 0x3fb8aa3b, v72
	v_exp_f32_e32 v146, v72
	v_sub_f32_e32 v71, v71, v113
	v_mul_f32_e32 v142, 0x3fb8aa3b, v71
	v_pk_add_f32 v[70:71], v[124:125], 0 op_sel_hi:[1,0]
	v_and_b32_sdwa v73, v136, v186 dst_sel:DWORD dst_unused:UNUSED_PAD src0_sel:WORD_1 src1_sel:DWORD
	v_pk_add_f32 v[70:71], v[122:123], v[70:71]
	v_add3_u32 v76, v136, v73, s31
	v_and_b32_sdwa v73, v146, v186 dst_sel:DWORD dst_unused:UNUSED_PAD src0_sel:WORD_1 src1_sel:DWORD
	v_and_b32_sdwa v77, v134, v186 dst_sel:DWORD dst_unused:UNUSED_PAD src0_sel:WORD_1 src1_sel:DWORD
	v_pk_add_f32 v[68:69], v[68:69], v[70:71]
	v_sub_f32_e32 v70, v89, v113
	v_and_b32_sdwa v72, v132, v186 dst_sel:DWORD dst_unused:UNUSED_PAD src0_sel:WORD_1 src1_sel:DWORD
	v_add3_u32 v73, v146, v73, s31
	v_add3_u32 v77, v134, v77, s31
	v_mul_f32_e32 v70, 0x3fb8aa3b, v70
	v_add3_u32 v72, v132, v72, s31
	v_and_b32_e32 v73, 0xffff0000, v73
	v_and_b32_e32 v77, 0xffff0000, v77
	v_exp_f32_e32 v130, v70
	v_sub_f32_e32 v70, v90, v113
	v_or_b32_sdwa v73, v73, v72 dst_sel:DWORD dst_unused:UNUSED_PAD src0_sel:DWORD src1_sel:WORD_1
	v_or_b32_sdwa v72, v77, v76 dst_sel:DWORD dst_unused:UNUSED_PAD src0_sel:DWORD src1_sel:WORD_1
	v_sub_f32_e32 v76, v88, v113
	v_mul_f32_e32 v70, 0x3fb8aa3b, v70
	v_mul_f32_e32 v76, 0x3fb8aa3b, v76
	v_exp_f32_e32 v128, v70
	v_sub_f32_e32 v70, v91, v113
	v_exp_f32_e32 v144, v76
	v_mul_f32_e32 v70, 0x3fb8aa3b, v70
	v_exp_f32_e32 v148, v70
	v_and_b32_sdwa v77, v130, v186 dst_sel:DWORD dst_unused:UNUSED_PAD src0_sel:WORD_1 src1_sel:DWORD
	v_and_b32_sdwa v71, v144, v186 dst_sel:DWORD dst_unused:UNUSED_PAD src0_sel:WORD_1 src1_sel:DWORD
	v_add3_u32 v76, v144, v71, s31
	v_and_b32_sdwa v71, v148, v186 dst_sel:DWORD dst_unused:UNUSED_PAD src0_sel:WORD_1 src1_sel:DWORD
	v_and_b32_sdwa v70, v128, v186 dst_sel:DWORD dst_unused:UNUSED_PAD src0_sel:WORD_1 src1_sel:DWORD
	v_add3_u32 v71, v148, v71, s31
	v_add3_u32 v77, v130, v77, s31
	v_add3_u32 v70, v128, v70, s31
	v_and_b32_e32 v71, 0xffff0000, v71
	v_and_b32_e32 v77, 0xffff0000, v77
	v_or_b32_sdwa v71, v71, v70 dst_sel:DWORD dst_unused:UNUSED_PAD src0_sel:DWORD src1_sel:WORD_1
	v_or_b32_sdwa v70, v77, v76 dst_sel:DWORD dst_unused:UNUSED_PAD src0_sel:DWORD src1_sel:WORD_1
	ds_write2_b64 v205, v[72:73], v[70:71] offset0:8 offset1:12
	v_sub_f32_e32 v70, v84, v113
	v_mul_f32_e32 v70, 0x3fb8aa3b, v70
	v_exp_f32_e32 v154, v70
	v_sub_f32_e32 v70, v85, v113
	v_mul_f32_e32 v70, 0x3fb8aa3b, v70
	v_exp_f32_e32 v152, v70
	v_sub_f32_e32 v70, v86, v113
	v_mul_f32_e32 v70, 0x3fb8aa3b, v70
	v_exp_f32_e32 v150, v70
	v_sub_f32_e32 v70, v87, v113
	v_mul_f32_e32 v70, 0x3fb8aa3b, v70
	v_exp_f32_e32 v162, v70
	v_and_b32_sdwa v71, v154, v186 dst_sel:DWORD dst_unused:UNUSED_PAD src0_sel:WORD_1 src1_sel:DWORD
	v_add3_u32 v72, v154, v71, s31
	v_and_b32_sdwa v73, v152, v186 dst_sel:DWORD dst_unused:UNUSED_PAD src0_sel:WORD_1 src1_sel:DWORD
; #define LAS __attribute__((address_space(3)))
; DI unsigned pk2(float lo, float hi) { return f2bf(lo) | (f2bf(hi) << 16); }
; DI void attn_tile(int j, int tile, LAS unsigned char* lds) {
;     ...
;             for (int nt = 0; nt < 8; ++nt) { float o[4];
; #pragma unroll
;                 for (int e = 0; e < 4; ++e) { o[e] = __expf(s[nt][e] - mn); rs += o[e]; }
;                 u32x2 w2; w2.x = pk2(o[0], o[1]); w2.y = pk2(o[2], o[3]);
;                 *(LAS u32x2*)(Ps + qi * 136 + nt * 16 + fq * 4) = w2; }
;             rs += __shfl_xor(rs, 16); rs += __shfl_xor(rs, 32);
;             lr[g] = lr[g] * alpha + rs; mr[g] = mn;
	v_and_b32_sdwa v71, v162, v186 dst_sel:DWORD dst_unused:UNUSED_PAD src0_sel:WORD_1 src1_sel:DWORD
	v_and_b32_sdwa v70, v150, v186 dst_sel:DWORD dst_unused:UNUSED_PAD src0_sel:WORD_1 src1_sel:DWORD
	v_add3_u32 v71, v162, v71, s31
	v_add3_u32 v73, v152, v73, s31
	v_add3_u32 v70, v150, v70, s31
	v_and_b32_e32 v71, 0xffff0000, v71
	v_and_b32_e32 v73, 0xffff0000, v73
	v_or_b32_sdwa v71, v71, v70 dst_sel:DWORD dst_unused:UNUSED_PAD src0_sel:DWORD src1_sel:WORD_1
	v_or_b32_sdwa v70, v73, v72 dst_sel:DWORD dst_unused:UNUSED_PAD src0_sel:DWORD src1_sel:WORD_1
	v_sub_f32_e32 v72, v80, v113
	v_mul_f32_e32 v72, 0x3fb8aa3b, v72
	v_exp_f32_e32 v158, v72
	v_sub_f32_e32 v72, v81, v113
	v_mul_f32_e32 v72, 0x3fb8aa3b, v72
	v_exp_f32_e32 v156, v72
	v_sub_f32_e32 v72, v82, v113
	v_mul_f32_e32 v72, 0x3fb8aa3b, v72
	v_exp_f32_e32 v160, v72
	v_sub_f32_e32 v72, v83, v113
	v_mul_f32_e32 v72, 0x3fb8aa3b, v72
	v_exp_f32_e32 v170, v72
	v_and_b32_sdwa v73, v158, v186 dst_sel:DWORD dst_unused:UNUSED_PAD src0_sel:WORD_1 src1_sel:DWORD
	v_add3_u32 v76, v158, v73, s31
	v_and_b32_sdwa v77, v156, v186 dst_sel:DWORD dst_unused:UNUSED_PAD src0_sel:WORD_1 src1_sel:DWORD
	v_and_b32_sdwa v73, v170, v186 dst_sel:DWORD dst_unused:UNUSED_PAD src0_sel:WORD_1 src1_sel:DWORD
	v_and_b32_sdwa v72, v160, v186 dst_sel:DWORD dst_unused:UNUSED_PAD src0_sel:WORD_1 src1_sel:DWORD
	v_add3_u32 v73, v170, v73, s31
	v_add3_u32 v77, v156, v77, s31
	v_add3_u32 v72, v160, v72, s31
	v_and_b32_e32 v73, 0xffff0000, v73
	v_and_b32_e32 v77, 0xffff0000, v77
	v_or_b32_sdwa v73, v73, v72 dst_sel:DWORD dst_unused:UNUSED_PAD src0_sel:DWORD src1_sel:WORD_1
	v_or_b32_sdwa v72, v77, v76 dst_sel:DWORD dst_unused:UNUSED_PAD src0_sel:DWORD src1_sel:WORD_1
	ds_write2_b64 v205, v[70:71], v[72:73] offset0:16 offset1:20
	v_sub_f32_e32 v70, v102, v113
	v_mul_f32_e32 v70, 0x3fb8aa3b, v70
	v_pk_add_f32 v[68:69], v[114:115], v[68:69]
	v_exp_f32_e32 v164, v70
	v_sub_f32_e32 v70, v140, v113
	v_pk_add_f32 v[68:69], v[120:121], v[68:69]
	v_mul_f32_e32 v70, 0x3fb8aa3b, v70
	v_pk_add_f32 v[68:69], v[118:119], v[68:69]
	v_exp_f32_e32 v166, v70
	v_sub_f32_e32 v70, v74, v113
	v_pk_add_f32 v[68:69], v[116:117], v[68:69]
	v_mul_f32_e32 v70, 0x3fb8aa3b, v70
	v_pk_add_f32 v[68:69], v[126:127], v[68:69]
	v_exp_f32_e32 v168, v70
	v_sub_f32_e32 v70, v75, v113
	v_pk_add_f32 v[68:69], v[136:137], v[68:69]
	v_mul_f32_e32 v70, 0x3fb8aa3b, v70
	v_pk_add_f32 v[68:69], v[134:135], v[68:69]
	v_exp_f32_e32 v172, v70
	v_pk_add_f32 v[68:69], v[132:133], v[68:69]
	v_and_b32_sdwa v71, v164, v186 dst_sel:DWORD dst_unused:UNUSED_PAD src0_sel:WORD_1 src1_sel:DWORD
	v_pk_add_f32 v[68:69], v[146:147], v[68:69]
	v_add3_u32 v72, v164, v71, s31
	v_pk_add_f32 v[68:69], v[144:145], v[68:69]
	v_and_b32_sdwa v71, v172, v186 dst_sel:DWORD dst_unused:UNUSED_PAD src0_sel:WORD_1 src1_sel:DWORD
	v_pk_add_f32 v[68:69], v[130:131], v[68:69]
	v_and_b32_sdwa v73, v166, v186 dst_sel:DWORD dst_unused:UNUSED_PAD src0_sel:WORD_1 src1_sel:DWORD
	v_pk_add_f32 v[68:69], v[128:129], v[68:69]
	v_and_b32_sdwa v70, v168, v186 dst_sel:DWORD dst_unused:UNUSED_PAD src0_sel:WORD_1 src1_sel:DWORD
	v_add3_u32 v71, v172, v71, s31
	v_add3_u32 v73, v166, v73, s31
	v_pk_add_f32 v[68:69], v[148:149], v[68:69]
	v_add3_u32 v70, v168, v70, s31
	v_and_b32_e32 v71, 0xffff0000, v71
	v_and_b32_e32 v73, 0xffff0000, v73
	v_pk_add_f32 v[68:69], v[154:155], v[68:69]
	v_or_b32_sdwa v71, v71, v70 dst_sel:DWORD dst_unused:UNUSED_PAD src0_sel:DWORD src1_sel:WORD_1
	v_or_b32_sdwa v70, v73, v72 dst_sel:DWORD dst_unused:UNUSED_PAD src0_sel:DWORD src1_sel:WORD_1
	v_sub_f32_e32 v72, v100, v113
	v_pk_add_f32 v[68:69], v[152:153], v[68:69]
	v_mul_f32_e32 v72, 0x3fb8aa3b, v72
	v_pk_add_f32 v[68:69], v[150:151], v[68:69]
	v_exp_f32_e32 v174, v72
	v_sub_f32_e32 v72, v141, v113
	v_pk_add_f32 v[68:69], v[162:163], v[68:69]
	v_mul_f32_e32 v72, 0x3fb8aa3b, v72
	v_pk_add_f32 v[68:69], v[158:159], v[68:69]
	v_exp_f32_e32 v176, v72
	v_sub_f32_e32 v72, v78, v113
	v_pk_add_f32 v[68:69], v[156:157], v[68:69]
	v_mul_f32_e32 v72, 0x3fb8aa3b, v72
	v_pk_add_f32 v[68:69], v[160:161], v[68:69]
	v_exp_f32_e32 v178, v72
	v_sub_f32_e32 v72, v79, v113
	v_pk_add_f32 v[68:69], v[170:171], v[68:69]
	v_mul_f32_e32 v72, 0x3fb8aa3b, v72
	v_exp_f32_e32 v180, v72
	v_pk_add_f32 v[68:69], v[164:165], v[68:69]
	v_and_b32_sdwa v73, v174, v186 dst_sel:DWORD dst_unused:UNUSED_PAD src0_sel:WORD_1 src1_sel:DWORD
	v_pk_add_f32 v[68:69], v[166:167], v[68:69]
	v_add3_u32 v74, v174, v73, s31
	v_pk_add_f32 v[68:69], v[168:169], v[68:69]
	v_and_b32_sdwa v73, v180, v186 dst_sel:DWORD dst_unused:UNUSED_PAD src0_sel:WORD_1 src1_sel:DWORD
	v_pk_add_f32 v[68:69], v[172:173], v[68:69]
	v_and_b32_sdwa v75, v176, v186 dst_sel:DWORD dst_unused:UNUSED_PAD src0_sel:WORD_1 src1_sel:DWORD
	v_pk_add_f32 v[68:69], v[174:175], v[68:69]
	v_and_b32_sdwa v72, v178, v186 dst_sel:DWORD dst_unused:UNUSED_PAD src0_sel:WORD_1 src1_sel:DWORD
	v_add3_u32 v73, v180, v73, s31
	v_add3_u32 v75, v176, v75, s31
	v_pk_add_f32 v[68:69], v[176:177], v[68:69]
	v_add3_u32 v72, v178, v72, s31
	v_and_b32_e32 v73, 0xffff0000, v73
	v_and_b32_e32 v75, 0xffff0000, v75
	v_pk_add_f32 v[68:69], v[178:179], v[68:69]
	v_or_b32_sdwa v73, v73, v72 dst_sel:DWORD dst_unused:UNUSED_PAD src0_sel:DWORD src1_sel:WORD_1
	v_or_b32_sdwa v72, v75, v74 dst_sel:DWORD dst_unused:UNUSED_PAD src0_sel:DWORD src1_sel:WORD_1
	v_pk_add_f32 v[68:69], v[180:181], v[68:69]
	ds_write2_b64 v205, v[70:71], v[72:73] offset0:24 offset1:28
	ds_bpermute_b32 v73, v109, v69
	ds_bpermute_b32 v72, v109, v68
	v_exp_f32_e32 v70, v142
	v_mov_b32_e32 v71, v0
	s_waitcnt lgkmcnt(0)
; DI void attn_tile(int j, int tile, LAS unsigned char* lds) {
;     ...
;             rs += __shfl_xor(rs, 16); rs += __shfl_xor(rs, 32);
;             lr[g] = lr[g] * alpha + rs; mr[g] = mn;
; #pragma unroll
;             for (int i = 0; i < 4; ++i) O[g][i] *= alpha;
;             mm16<4, 4>(Ps + wave * 16 * 136, 136, VTs, 136, O[g], fr, fq);
	v_pk_add_f32 v[68:69], v[68:69], v[72:73]
	ds_bpermute_b32 v73, v139, v69
	ds_bpermute_b32 v72, v139, v68
	v_pk_mul_f32 v[30:31], v[30:31], v[70:71] op_sel_hi:[1,0]
	v_pk_mul_f32 v[28:29], v[28:29], v[70:71] op_sel_hi:[1,0]
	v_pk_mul_f32 v[26:27], v[26:27], v[70:71] op_sel_hi:[1,0]
	v_pk_mul_f32 v[24:25], v[24:25], v[70:71] op_sel_hi:[1,0]
	s_waitcnt lgkmcnt(0)
	v_pk_add_f32 v[68:69], v[68:69], v[72:73]
	v_pk_mul_f32 v[22:23], v[22:23], v[70:71] op_sel_hi:[1,0]
	v_pk_fma_f32 v[2:3], v[2:3], v[70:71], v[68:69]
	v_pk_mul_f32 v[20:21], v[20:21], v[70:71] op_sel_hi:[1,0]
	v_pk_mul_f32 v[34:35], v[34:35], v[70:71] op_sel_hi:[1,0]
	v_pk_mul_f32 v[32:33], v[32:33], v[70:71] op_sel_hi:[1,0]
	ds_read_b128 v[68:71], v202
	ds_read_b128 v[72:75], v206
	s_waitcnt lgkmcnt(0)
	v_mfma_f32_16x16x32_bf16 v[28:31], v[72:75], v[68:71], v[28:31]
	ds_read_b128 v[72:75], v206 offset:4352
	s_waitcnt lgkmcnt(0)
	v_mfma_f32_16x16x32_bf16 v[24:27], v[72:75], v[68:71], v[24:27]
	ds_read_b128 v[72:75], v206 offset:8704
	s_waitcnt lgkmcnt(0)
	v_mfma_f32_16x16x32_bf16 v[20:23], v[72:75], v[68:71], v[20:23]
	ds_read_b128 v[72:75], v206 offset:13056
	s_waitcnt lgkmcnt(0)
	v_mfma_f32_16x16x32_bf16 v[32:35], v[72:75], v[68:71], v[32:35]
	ds_read_b128 v[68:71], v202 offset:64
	ds_read_b128 v[72:75], v206 offset:64
	s_waitcnt lgkmcnt(0)
	v_mfma_f32_16x16x32_bf16 v[28:31], v[72:75], v[68:71], v[28:31]
	ds_read_b128 v[72:75], v206 offset:4416
	s_waitcnt lgkmcnt(0)
	v_mfma_f32_16x16x32_bf16 v[24:27], v[72:75], v[68:71], v[24:27]
	ds_read_b128 v[72:75], v206 offset:8768
	s_waitcnt lgkmcnt(0)
	v_mfma_f32_16x16x32_bf16 v[20:23], v[72:75], v[68:71], v[20:23]
	ds_read_b128 v[72:75], v206 offset:13120
	s_waitcnt lgkmcnt(0)
	v_mfma_f32_16x16x32_bf16 v[32:35], v[72:75], v[68:71], v[32:35]
	ds_read_b128 v[68:71], v202 offset:128
	ds_read_b128 v[72:75], v206 offset:128
	s_waitcnt lgkmcnt(0)
	v_mfma_f32_16x16x32_bf16 v[28:31], v[72:75], v[68:71], v[28:31]
	ds_read_b128 v[72:75], v206 offset:4480
	s_waitcnt lgkmcnt(0)
	v_mfma_f32_16x16x32_bf16 v[24:27], v[72:75], v[68:71], v[24:27]
	ds_read_b128 v[72:75], v206 offset:8832
	s_waitcnt lgkmcnt(0)
	v_mfma_f32_16x16x32_bf16 v[20:23], v[72:75], v[68:71], v[20:23]
	ds_read_b128 v[72:75], v206 offset:13184
	s_waitcnt lgkmcnt(0)
	v_mfma_f32_16x16x32_bf16 v[32:35], v[72:75], v[68:71], v[32:35]
	ds_read_b128 v[68:71], v202 offset:192
	ds_read_b128 v[72:75], v206 offset:192
	s_waitcnt lgkmcnt(0)
	v_mfma_f32_16x16x32_bf16 v[28:31], v[72:75], v[68:71], v[28:31]
	ds_read_b128 v[72:75], v206 offset:4544
	s_waitcnt lgkmcnt(0)
	v_mfma_f32_16x16x32_bf16 v[24:27], v[72:75], v[68:71], v[24:27]
	ds_read_b128 v[72:75], v206 offset:8896
	s_waitcnt lgkmcnt(0)
	v_mfma_f32_16x16x32_bf16 v[20:23], v[72:75], v[68:71], v[20:23]
	ds_read_b128 v[72:75], v206 offset:13248
	s_waitcnt lgkmcnt(0)
	v_mfma_f32_16x16x32_bf16 v[32:35], v[72:75], v[68:71], v[32:35]
	v_mov_b64_e32 v[68:69], v[110:111]
	v_mov_b64_e32 v[70:71], v[112:113]

; #define LAS __attribute__((address_space(3)))
; DI float red4(float x) { x += dppmov<0xB1>(x); x += dppmov<0x4E>(x); return x; }
; DI int tid_opaque() { int t = threadIdx.x; asm volatile("" : "+v"(t)); return t; }
; DI void attn_load_head(const bf16_t* Pb, int coloff, int b, int t0, const float* g, bool rope, float scale, const float* tab, LAS bf16_t* dst) {
;     const int tid = tid_opaque(), row = tid >> 2, q4 = tid & 3; const int t = t0 + row; const size_t mrow = (size_t)b * T + t;
;     const bf16_t* src = Pb + mrow * PW + coloff;
;     float y[4][4]; float ss = 0.f;
; #pragma unroll
;     for (int c = 0; c < 4; ++c) { const u32x2 u = *(const u32x2*)(src + c * 16 + q4 * 4); y[c][0] = bflo(u.x); y[c][1] = bfhi(u.x); y[c][2] = bflo(u.y); y[c][3] = bfhi(u.y);
; #pragma unroll
;         for (int e = 0; e < 4; ++e) ss += y[c][e] * y[c][e]; }
;     ss = red4(ss); const float rstd = rsqrtf(ss * (1.f / 64.f) + 1e-6f);
; #pragma unroll
;     for (int c = 0; c < 4; ++c)
; #pragma unroll
;         for (int e = 0; e < 4; ++e) y[c][e] = y[c][e] * rstd * g[c * 16 + q4 * 4 + e];
;     if (rope) { const int pos = t - LC, rp = pos >> 6, cp = pos & 63;
; #pragma unroll
;         for (int e = 0; e < 4; ++e) { const int i = q4 * 4 + e;
;             { const float co = tab[rp * 16 + i], si = tab[1024 + rp * 16 + i]; const float x1 = y[0][e], x2 = y[1][e]; y[0][e] = x1 * co - x2 * si; y[1][e] = x1 * si + x2 * co; }
;             { const float co = tab[cp * 16 + i], si = tab[1024 + cp * 16 + i]; const float x1 = y[2][e], x2 = y[3][e]; y[2][e] = x1 * co - x2 * si; y[3][e] = x1 * si + x2 * co; } } }
.LBB0_614:
	v_mov_b32_e32 v0, v182
	s_waitcnt lgkmcnt(0)
	s_barrier
	v_mov_b64_e32 v[74:75], s[16:17]
	v_ashrrev_i32_e32 v90, 2, v0
	v_add_u32_e32 v88, s20, v90
	v_ashrrev_i32_e32 v89, 31, v88
	v_lshl_add_u64 v[72:73], s[12:13], 0, v[88:89]
	v_mad_u64_u32 v[74:75], s[2:3], v72, s78, v[74:75]
	v_and_b32_e32 v91, 3, v0
	v_mov_b32_e32 v0, v75
	v_mad_u64_u32 v[72:73], s[2:3], v73, s78, v[0:1]
	v_mov_b32_e32 v75, v72
	v_lshlrev_b32_e32 v0, 3, v91
	v_lshl_add_u64 v[72:73], v[74:75], 0, v[0:1]
	s_mov_b64 s[2:3], 0x1400
	s_movk_i32 s26, 0x1000
	v_lshl_add_u64 v[74:75], v[72:73], 0, s[2:3]
	v_add_co_u32_e32 v72, vcc, s26, v72
	global_load_dwordx2 v[80:81], v[74:75], off offset:64
	global_load_dwordx2 v[82:83], v[74:75], off offset:96
	v_addc_co_u32_e32 v73, vcc, 0, v73, vcc
	global_load_dwordx2 v[84:85], v[72:73], off offset:1024
	global_load_dwordx2 v[86:87], v[74:75], off offset:32
	v_lshlrev_b32_e32 v89, 4, v91
	global_load_dwordx4 v[72:75], v89, s[14:15]
	global_load_dwordx4 v[76:79], v89, s[14:15] offset:64
	global_load_dwordx4 v[92:95], v89, s[14:15] offset:128
	global_load_dwordx4 v[96:99], v89, s[14:15] offset:192
	s_mov_b32 s2, 0x800000
	s_andn2_b64 vcc, exec, s[22:23]
	s_waitcnt vmcnt(7)
	v_and_b32_e32 v101, 0xffff0000, v81
	v_lshlrev_b32_e32 v100, 16, v81
	v_and_b32_e32 v81, 0xffff0000, v80
	s_waitcnt vmcnt(5)
	v_and_b32_e32 v111, 0xffff0000, v85
	v_lshlrev_b32_e32 v110, 16, v85
	v_and_b32_e32 v85, 0xffff0000, v84
	v_lshlrev_b32_e32 v84, 16, v84
	v_pk_mul_f32 v[126:127], v[84:85], v[84:85]
	v_pk_mul_f32 v[122:123], v[110:111], v[110:111]
	v_add_f32_e32 v89, v126, v127
	s_waitcnt vmcnt(4)
	v_and_b32_e32 v113, 0xffff0000, v87
	v_lshlrev_b32_e32 v112, 16, v87
	v_and_b32_e32 v87, 0xffff0000, v86
	v_lshlrev_b32_e32 v86, 16, v86
	v_add_f32_e32 v89, v122, v89
	v_pk_mul_f32 v[128:129], v[86:87], v[86:87]
	v_add_f32_e32 v89, v123, v89
	v_add_f32_e32 v89, v128, v89
	v_pk_mul_f32 v[124:125], v[112:113], v[112:113]
	v_add_f32_e32 v89, v129, v89
	v_lshlrev_b32_e32 v80, 16, v80
	v_add_f32_e32 v89, v124, v89
	v_pk_mul_f32 v[118:119], v[80:81], v[80:81]
	v_add_f32_e32 v89, v125, v89
	v_add_f32_e32 v89, v118, v89
	v_pk_mul_f32 v[114:115], v[100:101], v[100:101]
	v_add_f32_e32 v89, v119, v89
	v_and_b32_e32 v103, 0xffff0000, v83
	v_lshlrev_b32_e32 v102, 16, v83
	v_and_b32_e32 v83, 0xffff0000, v82
	v_lshlrev_b32_e32 v82, 16, v82
	v_add_f32_e32 v89, v114, v89
	v_pk_mul_f32 v[120:121], v[82:83], v[82:83]
	v_add_f32_e32 v89, v115, v89
	v_add_f32_e32 v89, v120, v89
	v_pk_mul_f32 v[116:117], v[102:103], v[102:103]
	v_add_f32_e32 v89, v121, v89
	v_add_f32_e32 v89, v116, v89
	v_add_f32_e32 v89, v117, v89
	s_nop 1
	v_add_f32_dpp v89, v89, v89 quad_perm:[1,0,3,2] row_mask:0xf bank_mask:0xf bound_ctrl:1
	s_nop 1
	v_add_f32_dpp v89, v89, v89 quad_perm:[2,3,0,1] row_mask:0xf bank_mask:0xf bound_ctrl:1
	v_fmamk_f32 v89, v89, 0x3c800000, v183
	v_mul_f32_e32 v109, 0x4b800000, v89
	v_cmp_gt_f32_e64 s[4:5], s2, v89
	s_nop 1
	v_cndmask_b32_e64 v89, v89, v109, s[4:5]
	v_rsq_f32_e32 v89, v89
	s_nop 0
	v_mul_f32_e32 v109, 0x45800000, v89
	v_cndmask_b32_e64 v114, v89, v109, s[4:5]
	v_pk_mul_f32 v[84:85], v[114:115], v[84:85] op_sel_hi:[0,1]
	v_pk_mul_f32 v[110:111], v[114:115], v[110:111] op_sel_hi:[0,1]
	v_pk_mul_f32 v[116:117], v[114:115], v[86:87] op_sel_hi:[0,1]
	v_pk_mul_f32 v[112:113], v[114:115], v[112:113] op_sel_hi:[0,1]
	v_pk_mul_f32 v[118:119], v[114:115], v[80:81] op_sel_hi:[0,1]
	v_pk_mul_f32 v[100:101], v[114:115], v[100:101] op_sel_hi:[0,1]
	v_pk_mul_f32 v[120:121], v[114:115], v[82:83] op_sel_hi:[0,1]
	v_pk_mul_f32 v[102:103], v[114:115], v[102:103] op_sel_hi:[0,1]
	s_waitcnt vmcnt(3)
	v_pk_mul_f32 v[84:85], v[72:73], v[84:85]
	v_pk_mul_f32 v[86:87], v[74:75], v[110:111]
	s_waitcnt vmcnt(2)
	v_pk_mul_f32 v[80:81], v[76:77], v[116:117]
	v_pk_mul_f32 v[82:83], v[78:79], v[112:113]
	s_waitcnt vmcnt(1)
	v_pk_mul_f32 v[76:77], v[92:93], v[118:119]
	v_pk_mul_f32 v[78:79], v[94:95], v[100:101]
	s_waitcnt vmcnt(0)
	v_pk_mul_f32 v[72:73], v[96:97], v[120:121]
	v_pk_mul_f32 v[74:75], v[98:99], v[102:103]
	s_cbranch_vccnz .LBB0_609
	v_add_u32_e32 v89, 0xffffff00, v88
	v_lshlrev_b32_e32 v91, 2, v91
	v_ashrrev_i32_e32 v89, 2, v89
	v_lshlrev_b32_e32 v94, 4, v88
	v_and_or_b32 v88, v89, -16, v91
	v_ashrrev_i32_e32 v89, 31, v88
	v_lshl_add_u64 v[92:93], v[88:89], 2, s[8:9]
	v_add_u32_e32 v88, 0x400, v88
	v_ashrrev_i32_e32 v89, 31, v88
	v_lshl_add_u64 v[88:89], v[88:89], 2, s[8:9]
	v_and_or_b32 v91, v94, s1, v91
	global_load_dwordx4 v[92:95], v[92:93], off
	s_nop 0
	global_load_dwordx4 v[96:99], v[88:89], off
	v_lshlrev_b32_e32 v100, 2, v91
	v_mov_b32_e32 v101, v1
	v_lshl_add_u64 v[110:111], s[8:9], 0, v[100:101]
	global_load_dwordx4 v[100:103], v100, s[8:9]
	v_add_co_u32_e32 v88, vcc, s26, v110
	s_nop 1
	v_addc_co_u32_e32 v89, vcc, 0, v111, vcc
	global_load_dwordx4 v[110:113], v[88:89], off
	s_waitcnt vmcnt(2)
	v_pk_mul_f32 v[88:89], v[84:85], v[96:97]
	v_pk_mul_f32 v[96:97], v[80:81], v[96:97]
	v_pk_fma_f32 v[80:81], v[80:81], v[92:93], v[88:89]
	v_pk_fma_f32 v[84:85], v[84:85], v[92:93], v[96:97] neg_lo:[0,0,1] neg_hi:[0,0,1]
	s_nop 0
	s_waitcnt vmcnt(0)
	v_pk_mul_f32 v[88:89], v[76:77], v[110:111]
	v_pk_mul_f32 v[92:93], v[72:73], v[110:111]
	v_pk_fma_f32 v[72:73], v[72:73], v[100:101], v[88:89]
	v_pk_fma_f32 v[76:77], v[76:77], v[100:101], v[92:93] neg_lo:[0,0,1] neg_hi:[0,0,1]
	v_pk_mul_f32 v[88:89], v[86:87], v[98:99]
	v_pk_mul_f32 v[92:93], v[82:83], v[98:99]
	v_pk_fma_f32 v[82:83], v[82:83], v[94:95], v[88:89]
	v_pk_fma_f32 v[86:87], v[86:87], v[94:95], v[92:93] neg_lo:[0,0,1] neg_hi:[0,0,1]
	v_pk_mul_f32 v[88:89], v[78:79], v[112:113]
	v_pk_mul_f32 v[92:93], v[74:75], v[112:113]
	v_pk_fma_f32 v[74:75], v[74:75], v[102:103], v[88:89]
	v_pk_fma_f32 v[78:79], v[78:79], v[102:103], v[92:93] neg_lo:[0,0,1] neg_hi:[0,0,1]
	s_branch .LBB0_609
